# GEMM K-loops: LDS-DMA pieces per load section rebalanced from 2/6/2/6 to 2/4/4/6 (last two pieces of section 2 issued at the head of section 3, section-2 wait vmcnt(8)->(6))
# speedup vs baseline: 1.0398x; 1.0328x over previous
.LBB0_157:
	ds_read_b128 v[154:157], v151
	ds_read_b128 v[158:161], v151 offset:1024
	ds_read_b128 v[162:165], v151 offset:2048
	ds_read_b128 v[166:169], v151 offset:3072
	ds_read_b128 v[170:173], v152
	ds_read_b128 v[174:177], v152 offset:1024
	ds_read_b128 v[178:181], v152 offset:2048
	ds_read_b128 v[182:185], v152 offset:3072
	s_add_u32 s8, s26, 0xfffc0080
	s_addc_u32 s9, s27, -1
	s_cmp_eq_u32 s45, 12
	s_cselect_b32 s29, s13, s9
	s_cselect_b32 s28, s39, s8
	s_cselect_b32 s9, s11, s44
	s_cselect_b32 s8, s40, s41
	v_lshl_add_u64 v[144:145], s[26:27], 0, v[136:137]
	s_add_i32 m0, s16, 0xc000
	ds_read_b128 v[186:189], v153
	ds_read_b128 v[190:193], v153 offset:1024
	ds_read_b128 v[196:199], v153 offset:2048
	ds_read_b128 v[200:203], v153 offset:3072
	ds_read_b128 v[204:207], v153 offset:4096
	ds_read_b128 v[208:211], v153 offset:5120
	ds_read_b128 v[212:215], v153 offset:6144
	ds_read_b128 v[216:219], v153 offset:7168
	global_load_lds_dwordx4 v[144:145], off
	v_lshl_add_u64 v[144:145], s[26:27], 0, v[138:139]
	s_add_i32 m0, s16, 0xe000
	s_nop 0
	global_load_lds_dwordx4 v[144:145], off
	s_waitcnt vmcnt(8)
	s_waitcnt lgkmcnt(0)
	s_barrier
	s_setprio 1
	s_waitcnt lgkmcnt(0)
	v_mfma_f32_16x16x32_bf16 v[124:127], v[154:157], v[186:189], v[124:127]
	v_mfma_f32_16x16x32_bf16 v[120:123], v[162:165], v[186:189], v[120:123]
	v_mfma_f32_16x16x32_bf16 v[116:119], v[154:157], v[196:199], v[116:119]
	v_mfma_f32_16x16x32_bf16 v[108:111], v[162:165], v[196:199], v[108:111]
	v_mfma_f32_16x16x32_bf16 v[96:99], v[154:157], v[204:207], v[96:99]
	v_mfma_f32_16x16x32_bf16 v[88:91], v[162:165], v[204:207], v[88:91]
	v_mfma_f32_16x16x32_bf16 v[84:87], v[154:157], v[212:215], v[84:87]
	v_mfma_f32_16x16x32_bf16 v[76:79], v[162:165], v[212:215], v[76:79]
	v_mfma_f32_16x16x32_bf16 v[124:127], v[158:161], v[190:193], v[124:127]
	v_mfma_f32_16x16x32_bf16 v[120:123], v[166:169], v[190:193], v[120:123]
	v_mfma_f32_16x16x32_bf16 v[116:119], v[158:161], v[200:203], v[116:119]
	v_mfma_f32_16x16x32_bf16 v[108:111], v[166:169], v[200:203], v[108:111]
	v_mfma_f32_16x16x32_bf16 v[96:99], v[158:161], v[208:211], v[96:99]
	v_mfma_f32_16x16x32_bf16 v[88:91], v[166:169], v[208:211], v[88:91]
	v_mfma_f32_16x16x32_bf16 v[84:87], v[158:161], v[216:219], v[84:87]
	v_mfma_f32_16x16x32_bf16 v[76:79], v[166:169], v[216:219], v[76:79]
	s_setprio 0
	s_setprio 1
	v_mfma_f32_16x16x32_bf16 v[112:115], v[170:173], v[186:189], v[112:115]
	v_mfma_f32_16x16x32_bf16 v[104:107], v[178:181], v[186:189], v[104:107]
	v_mfma_f32_16x16x32_bf16 v[100:103], v[170:173], v[196:199], v[100:103]
	v_mfma_f32_16x16x32_bf16 v[92:95], v[178:181], v[196:199], v[92:95]
	v_mfma_f32_16x16x32_bf16 v[80:83], v[170:173], v[204:207], v[80:83]
	v_mfma_f32_16x16x32_bf16 v[72:75], v[178:181], v[204:207], v[72:75]
	v_mfma_f32_16x16x32_bf16 v[68:71], v[170:173], v[212:215], v[68:71]
	v_mfma_f32_16x16x32_bf16 v[64:67], v[178:181], v[212:215], v[64:67]
	v_mfma_f32_16x16x32_bf16 v[112:115], v[174:177], v[190:193], v[112:115]
	v_mfma_f32_16x16x32_bf16 v[104:107], v[182:185], v[190:193], v[104:107]
	v_mfma_f32_16x16x32_bf16 v[100:103], v[174:177], v[200:203], v[100:103]
	v_mfma_f32_16x16x32_bf16 v[92:95], v[182:185], v[200:203], v[92:95]
	v_mfma_f32_16x16x32_bf16 v[80:83], v[174:177], v[208:211], v[80:83]
	v_mfma_f32_16x16x32_bf16 v[72:75], v[182:185], v[208:211], v[72:75]
	v_mfma_f32_16x16x32_bf16 v[68:71], v[174:177], v[216:219], v[68:71]
	v_mfma_f32_16x16x32_bf16 v[64:67], v[182:185], v[216:219], v[64:67]
	s_setprio 0
	s_barrier
	s_add_i32 s46, s31, s3
	v_lshl_add_u64 v[144:145], s[8:9], 0, v[132:133]
	s_mov_b32 m0, s46
	ds_read_b128 v[186:189], v153 offset:16384
	ds_read_b128 v[190:193], v153 offset:17408
	ds_read_b128 v[196:199], v153 offset:18432
	ds_read_b128 v[200:203], v153 offset:19456
	ds_read_b128 v[204:207], v153 offset:20480
	ds_read_b128 v[208:211], v153 offset:21504
	ds_read_b128 v[212:215], v153 offset:22528
	ds_read_b128 v[216:219], v153 offset:23552
	global_load_lds_dwordx4 v[144:145], off
	s_add_i32 m0, s46, 0x2000
	s_add_u32 s46, s8, 0x40000
	v_lshl_add_u64 v[220:221], s[8:9], 0, v[128:129]
	s_addc_u32 s47, s9, 0
	s_add_i32 s48, s33, s3
	global_load_lds_dwordx4 v[220:221], off
	v_lshl_add_u64 v[222:223], s[46:47], 0, v[132:133]
	s_mov_b32 m0, s48
	v_lshl_add_u64 v[224:225], s[28:29], 0, v[130:131]
	global_load_lds_dwordx4 v[222:223], off
	v_lshl_add_u64 v[222:223], s[46:47], 0, v[128:129]
	s_add_i32 m0, s48, 0x2000
	s_nop 0
	global_load_lds_dwordx4 v[222:223], off
	s_waitcnt vmcnt(6)
	s_waitcnt lgkmcnt(0)
	s_barrier
	s_setprio 1
	s_waitcnt lgkmcnt(0)
	v_mfma_f32_16x16x32_bf16 v[60:63], v[154:157], v[186:189], v[60:63]
	v_mfma_f32_16x16x32_bf16 v[56:59], v[162:165], v[186:189], v[56:59]
	v_mfma_f32_16x16x32_bf16 v[52:55], v[154:157], v[196:199], v[52:55]
	v_mfma_f32_16x16x32_bf16 v[44:47], v[162:165], v[196:199], v[44:47]
	v_mfma_f32_16x16x32_bf16 v[32:35], v[154:157], v[204:207], v[32:35]
	v_mfma_f32_16x16x32_bf16 v[24:27], v[162:165], v[204:207], v[24:27]
	v_mfma_f32_16x16x32_bf16 v[20:23], v[154:157], v[212:215], v[20:23]
	v_mfma_f32_16x16x32_bf16 v[12:15], v[162:165], v[212:215], v[12:15]
	v_mfma_f32_16x16x32_bf16 v[60:63], v[158:161], v[190:193], v[60:63]
	v_mfma_f32_16x16x32_bf16 v[56:59], v[166:169], v[190:193], v[56:59]
	v_mfma_f32_16x16x32_bf16 v[52:55], v[158:161], v[200:203], v[52:55]
	v_mfma_f32_16x16x32_bf16 v[44:47], v[166:169], v[200:203], v[44:47]
	v_mfma_f32_16x16x32_bf16 v[32:35], v[158:161], v[208:211], v[32:35]
	v_mfma_f32_16x16x32_bf16 v[24:27], v[166:169], v[208:211], v[24:27]
	v_mfma_f32_16x16x32_bf16 v[20:23], v[158:161], v[216:219], v[20:23]
	v_mfma_f32_16x16x32_bf16 v[12:15], v[166:169], v[216:219], v[12:15]
	s_setprio 0
	s_setprio 1
	v_mfma_f32_16x16x32_bf16 v[48:51], v[170:173], v[186:189], v[48:51]
	v_mfma_f32_16x16x32_bf16 v[40:43], v[178:181], v[186:189], v[40:43]
	v_mfma_f32_16x16x32_bf16 v[36:39], v[170:173], v[196:199], v[36:39]
	v_mfma_f32_16x16x32_bf16 v[28:31], v[178:181], v[196:199], v[28:31]
	v_mfma_f32_16x16x32_bf16 v[16:19], v[170:173], v[204:207], v[16:19]
	v_mfma_f32_16x16x32_bf16 v[8:11], v[178:181], v[204:207], v[8:11]
	v_mfma_f32_16x16x32_bf16 v[4:7], v[170:173], v[212:215], v[4:7]
	v_mfma_f32_16x16x32_bf16 v[0:3], v[178:181], v[212:215], v[0:3]
	v_mfma_f32_16x16x32_bf16 v[48:51], v[174:177], v[190:193], v[48:51]
	v_mfma_f32_16x16x32_bf16 v[40:43], v[182:185], v[190:193], v[40:43]
	v_mfma_f32_16x16x32_bf16 v[36:39], v[174:177], v[200:203], v[36:39]
	v_mfma_f32_16x16x32_bf16 v[28:31], v[182:185], v[200:203], v[28:31]
	v_mfma_f32_16x16x32_bf16 v[16:19], v[174:177], v[208:211], v[16:19]
	v_mfma_f32_16x16x32_bf16 v[8:11], v[182:185], v[208:211], v[8:11]
	v_mfma_f32_16x16x32_bf16 v[4:7], v[174:177], v[216:219], v[4:7]
	v_mfma_f32_16x16x32_bf16 v[0:3], v[182:185], v[216:219], v[0:3]
	s_setprio 0
	s_barrier
	v_lshl_add_u64 v[222:223], s[28:29], 0, v[134:135]
	s_mov_b32 m0, s16
	s_nop 0
	global_load_lds_dwordx4 v[222:223], off
	s_mov_b32 m0, s17
	s_nop 0
	global_load_lds_dwordx4 v[224:225], off
	s_add_i32 s46, 0, 0x18000
	s_add_i32 s47, 0, 0x1c000
	v_add_u32_e32 v166, s46, v148
	v_add_u32_e32 v182, s47, v148
	ds_read_b128 v[154:157], v166
	ds_read_b128 v[158:161], v166 offset:1024
	ds_read_b128 v[162:165], v166 offset:2048
	ds_read_b128 v[166:169], v166 offset:3072
	ds_read_b128 v[170:173], v182
	ds_read_b128 v[174:177], v182 offset:1024
	ds_read_b128 v[178:181], v182 offset:2048
	ds_read_b128 v[182:185], v182 offset:3072
	s_add_u32 s28, s28, 0x40000
	s_addc_u32 s29, s29, 0
	s_mov_b32 m0, s18
	v_lshl_add_u64 v[226:227], s[28:29], 0, v[134:135]
	ds_read_b128 v[186:189], v153 offset:32768
	ds_read_b128 v[190:193], v153 offset:33792
	ds_read_b128 v[196:199], v153 offset:34816
	ds_read_b128 v[200:203], v153 offset:35840
	ds_read_b128 v[204:207], v153 offset:36864
	ds_read_b128 v[208:211], v153 offset:37888
	ds_read_b128 v[212:215], v153 offset:38912
	ds_read_b128 v[216:219], v153 offset:39936
	global_load_lds_dwordx4 v[226:227], off
	v_lshl_add_u64 v[226:227], s[28:29], 0, v[130:131]
	s_mov_b32 m0, s19
	s_nop 0
	global_load_lds_dwordx4 v[226:227], off
	s_waitcnt vmcnt(8)
	s_waitcnt lgkmcnt(0)
	s_barrier
	s_setprio 1
	s_waitcnt lgkmcnt(0)
	v_mfma_f32_16x16x32_bf16 v[124:127], v[154:157], v[186:189], v[124:127]
	v_mfma_f32_16x16x32_bf16 v[120:123], v[162:165], v[186:189], v[120:123]
	v_mfma_f32_16x16x32_bf16 v[116:119], v[154:157], v[196:199], v[116:119]
	v_mfma_f32_16x16x32_bf16 v[108:111], v[162:165], v[196:199], v[108:111]
	v_mfma_f32_16x16x32_bf16 v[96:99], v[154:157], v[204:207], v[96:99]
	v_mfma_f32_16x16x32_bf16 v[88:91], v[162:165], v[204:207], v[88:91]
	v_mfma_f32_16x16x32_bf16 v[84:87], v[154:157], v[212:215], v[84:87]
	v_mfma_f32_16x16x32_bf16 v[76:79], v[162:165], v[212:215], v[76:79]
	v_mfma_f32_16x16x32_bf16 v[124:127], v[158:161], v[190:193], v[124:127]
	v_mfma_f32_16x16x32_bf16 v[120:123], v[166:169], v[190:193], v[120:123]
	v_mfma_f32_16x16x32_bf16 v[116:119], v[158:161], v[200:203], v[116:119]
	v_mfma_f32_16x16x32_bf16 v[108:111], v[166:169], v[200:203], v[108:111]
	v_mfma_f32_16x16x32_bf16 v[96:99], v[158:161], v[208:211], v[96:99]
	v_mfma_f32_16x16x32_bf16 v[88:91], v[166:169], v[208:211], v[88:91]
	v_mfma_f32_16x16x32_bf16 v[84:87], v[158:161], v[216:219], v[84:87]
	v_mfma_f32_16x16x32_bf16 v[76:79], v[166:169], v[216:219], v[76:79]
	s_setprio 0
	s_setprio 1
	v_mfma_f32_16x16x32_bf16 v[112:115], v[170:173], v[186:189], v[112:115]
	v_mfma_f32_16x16x32_bf16 v[104:107], v[178:181], v[186:189], v[104:107]
	v_mfma_f32_16x16x32_bf16 v[100:103], v[170:173], v[196:199], v[100:103]
	v_mfma_f32_16x16x32_bf16 v[92:95], v[178:181], v[196:199], v[92:95]
	v_mfma_f32_16x16x32_bf16 v[80:83], v[170:173], v[204:207], v[80:83]
	v_mfma_f32_16x16x32_bf16 v[72:75], v[178:181], v[204:207], v[72:75]
	v_mfma_f32_16x16x32_bf16 v[68:71], v[170:173], v[212:215], v[68:71]
	v_mfma_f32_16x16x32_bf16 v[64:67], v[178:181], v[212:215], v[64:67]
	v_mfma_f32_16x16x32_bf16 v[112:115], v[174:177], v[190:193], v[112:115]
	v_mfma_f32_16x16x32_bf16 v[104:107], v[182:185], v[190:193], v[104:107]
	v_mfma_f32_16x16x32_bf16 v[100:103], v[174:177], v[200:203], v[100:103]
	v_mfma_f32_16x16x32_bf16 v[92:95], v[182:185], v[200:203], v[92:95]
	v_mfma_f32_16x16x32_bf16 v[80:83], v[174:177], v[208:211], v[80:83]
	v_mfma_f32_16x16x32_bf16 v[72:75], v[182:185], v[208:211], v[72:75]
	v_mfma_f32_16x16x32_bf16 v[68:71], v[174:177], v[216:219], v[68:71]
	v_mfma_f32_16x16x32_bf16 v[64:67], v[182:185], v[216:219], v[64:67]
	s_setprio 0
	s_barrier
	s_add_i32 s28, s46, s3
	v_lshl_add_u64 v[144:145], v[144:145], 0, s[4:5]
	s_mov_b32 m0, s28
	ds_read_b128 v[186:189], v153 offset:49152
	ds_read_b128 v[190:193], v153 offset:50176
	ds_read_b128 v[196:199], v153 offset:51200
	ds_read_b128 v[200:203], v153 offset:52224
	ds_read_b128 v[204:207], v153 offset:53248
	ds_read_b128 v[208:211], v153 offset:54272
	ds_read_b128 v[212:215], v153 offset:55296
	ds_read_b128 v[216:219], v153 offset:56320
	global_load_lds_dwordx4 v[144:145], off
	s_add_i32 m0, s28, 0x2000
	s_add_u32 s8, s8, 0x40080
	v_lshl_add_u64 v[144:145], v[220:221], 0, s[4:5]
	s_addc_u32 s9, s9, 0
	s_add_i32 s28, s47, s3
	global_load_lds_dwordx4 v[144:145], off
	v_lshl_add_u64 v[144:145], s[8:9], 0, v[132:133]
	s_mov_b32 m0, s28
	s_nop 0
	global_load_lds_dwordx4 v[144:145], off
	v_lshl_add_u64 v[144:145], s[8:9], 0, v[128:129]
	s_add_i32 m0, s28, 0x2000
	s_nop 0
	global_load_lds_dwordx4 v[144:145], off
	v_lshl_add_u64 v[144:145], v[222:223], 0, s[4:5]
	s_mov_b32 m0, s25
	s_nop 0
	global_load_lds_dwordx4 v[144:145], off
	v_lshl_add_u64 v[144:145], v[224:225], 0, s[4:5]
	s_mov_b32 m0, s30
	s_nop 0
	global_load_lds_dwordx4 v[144:145], off
	s_waitcnt vmcnt(8)
	s_waitcnt lgkmcnt(0)
	s_barrier
	s_setprio 1
	s_waitcnt lgkmcnt(0)
	v_mfma_f32_16x16x32_bf16 v[60:63], v[154:157], v[186:189], v[60:63]
	v_mfma_f32_16x16x32_bf16 v[56:59], v[162:165], v[186:189], v[56:59]
	v_mfma_f32_16x16x32_bf16 v[52:55], v[154:157], v[196:199], v[52:55]
	v_mfma_f32_16x16x32_bf16 v[44:47], v[162:165], v[196:199], v[44:47]
	v_mfma_f32_16x16x32_bf16 v[32:35], v[154:157], v[204:207], v[32:35]
	v_mfma_f32_16x16x32_bf16 v[24:27], v[162:165], v[204:207], v[24:27]
	v_mfma_f32_16x16x32_bf16 v[20:23], v[154:157], v[212:215], v[20:23]
	v_mfma_f32_16x16x32_bf16 v[12:15], v[162:165], v[212:215], v[12:15]
	v_mfma_f32_16x16x32_bf16 v[60:63], v[158:161], v[190:193], v[60:63]
	v_mfma_f32_16x16x32_bf16 v[56:59], v[166:169], v[190:193], v[56:59]
	v_mfma_f32_16x16x32_bf16 v[52:55], v[158:161], v[200:203], v[52:55]
	v_mfma_f32_16x16x32_bf16 v[44:47], v[166:169], v[200:203], v[44:47]
	v_mfma_f32_16x16x32_bf16 v[32:35], v[158:161], v[208:211], v[32:35]
	v_mfma_f32_16x16x32_bf16 v[24:27], v[166:169], v[208:211], v[24:27]
	v_mfma_f32_16x16x32_bf16 v[20:23], v[158:161], v[216:219], v[20:23]
	v_mfma_f32_16x16x32_bf16 v[12:15], v[166:169], v[216:219], v[12:15]
	s_setprio 0
	s_setprio 1
	v_mfma_f32_16x16x32_bf16 v[48:51], v[170:173], v[186:189], v[48:51]
	v_mfma_f32_16x16x32_bf16 v[40:43], v[178:181], v[186:189], v[40:43]
	v_mfma_f32_16x16x32_bf16 v[36:39], v[170:173], v[196:199], v[36:39]
	v_mfma_f32_16x16x32_bf16 v[28:31], v[178:181], v[196:199], v[28:31]
	v_mfma_f32_16x16x32_bf16 v[16:19], v[170:173], v[204:207], v[16:19]
	v_mfma_f32_16x16x32_bf16 v[8:11], v[178:181], v[204:207], v[8:11]
	v_mfma_f32_16x16x32_bf16 v[4:7], v[170:173], v[212:215], v[4:7]
	v_mfma_f32_16x16x32_bf16 v[0:3], v[178:181], v[212:215], v[0:3]
	v_mfma_f32_16x16x32_bf16 v[48:51], v[174:177], v[190:193], v[48:51]
	v_mfma_f32_16x16x32_bf16 v[40:43], v[182:185], v[190:193], v[40:43]
	v_mfma_f32_16x16x32_bf16 v[36:39], v[174:177], v[200:203], v[36:39]
	v_mfma_f32_16x16x32_bf16 v[28:31], v[182:185], v[200:203], v[28:31]
	v_mfma_f32_16x16x32_bf16 v[16:19], v[174:177], v[208:211], v[16:19]
	v_mfma_f32_16x16x32_bf16 v[8:11], v[182:185], v[208:211], v[8:11]
	v_mfma_f32_16x16x32_bf16 v[4:7], v[174:177], v[216:219], v[4:7]
	v_mfma_f32_16x16x32_bf16 v[0:3], v[182:185], v[216:219], v[0:3]
	s_setprio 0
	s_barrier
	s_add_i32 s45, s45, 2
	s_add_u32 s26, s26, 0x100
	s_addc_u32 s27, s27, 0
	s_add_u32 s41, s41, 0x100
	s_addc_u32 s44, s44, 0
	s_cmp_gt_u32 s45, 13
	s_cbranch_scc0 .LBB0_157
	s_and_b64 vcc, exec, s[6:7]
	s_cbranch_vccz .LBB0_160
	s_barrier

.LBB0_666:
	ds_read_b128 v[144:147], v153
	ds_read_b128 v[162:165], v153 offset:1024
	ds_read_b128 v[166:169], v153 offset:2048
	ds_read_b128 v[170:173], v153 offset:3072
	ds_read_b128 v[174:177], v154
	ds_read_b128 v[178:181], v154 offset:1024
	ds_read_b128 v[182:185], v154 offset:2048
	ds_read_b128 v[186:189], v154 offset:3072
	s_add_u32 s8, s38, 0xfffc0080
	s_addc_u32 s9, s39, -1
	s_cmp_eq_u32 s65, 12
	s_cselect_b32 s41, s27, s9
	s_cselect_b32 s40, s37, s8
	s_cselect_b32 s9, s25, s64
	s_cselect_b32 s8, s60, s61
	v_lshl_add_u64 v[156:157], s[38:39], 0, v[136:137]
	s_add_i32 m0, s4, 0xc000
	ds_read_b128 v[190:193], v155
	ds_read_b128 v[198:201], v155 offset:1024
	ds_read_b128 v[202:205], v155 offset:2048
	ds_read_b128 v[206:209], v155 offset:3072
	ds_read_b128 v[210:213], v155 offset:4096
	ds_read_b128 v[214:217], v155 offset:5120
	ds_read_b128 v[218:221], v155 offset:6144
	ds_read_b128 v[222:225], v155 offset:7168
	global_load_lds_dwordx4 v[156:157], off
	v_lshl_add_u64 v[156:157], s[38:39], 0, v[138:139]
	s_add_i32 m0, s4, 0xe000
	s_nop 0
	global_load_lds_dwordx4 v[156:157], off
	s_waitcnt vmcnt(8)
	s_waitcnt lgkmcnt(0)
	s_barrier
	s_setprio 1
	s_waitcnt lgkmcnt(0)
	v_mfma_f32_16x16x32_bf16 v[124:127], v[144:147], v[190:193], v[124:127]
	v_mfma_f32_16x16x32_bf16 v[120:123], v[166:169], v[190:193], v[120:123]
	v_mfma_f32_16x16x32_bf16 v[108:111], v[144:147], v[202:205], v[108:111]
	v_mfma_f32_16x16x32_bf16 v[104:107], v[166:169], v[202:205], v[104:107]
	v_mfma_f32_16x16x32_bf16 v[92:95], v[144:147], v[210:213], v[92:95]
	v_mfma_f32_16x16x32_bf16 v[88:91], v[166:169], v[210:213], v[88:91]
	v_mfma_f32_16x16x32_bf16 v[76:79], v[144:147], v[218:221], v[76:79]
	v_mfma_f32_16x16x32_bf16 v[72:75], v[166:169], v[218:221], v[72:75]
	v_mfma_f32_16x16x32_bf16 v[124:127], v[162:165], v[198:201], v[124:127]
	v_mfma_f32_16x16x32_bf16 v[120:123], v[170:173], v[198:201], v[120:123]
	v_mfma_f32_16x16x32_bf16 v[108:111], v[162:165], v[206:209], v[108:111]
	v_mfma_f32_16x16x32_bf16 v[104:107], v[170:173], v[206:209], v[104:107]
	v_mfma_f32_16x16x32_bf16 v[92:95], v[162:165], v[214:217], v[92:95]
	v_mfma_f32_16x16x32_bf16 v[88:91], v[170:173], v[214:217], v[88:91]
	v_mfma_f32_16x16x32_bf16 v[76:79], v[162:165], v[222:225], v[76:79]
	v_mfma_f32_16x16x32_bf16 v[72:75], v[170:173], v[222:225], v[72:75]
	s_setprio 0
	s_setprio 1
	v_mfma_f32_16x16x32_bf16 v[116:119], v[174:177], v[190:193], v[116:119]
	v_mfma_f32_16x16x32_bf16 v[112:115], v[182:185], v[190:193], v[112:115]
	v_mfma_f32_16x16x32_bf16 v[100:103], v[174:177], v[202:205], v[100:103]
	v_mfma_f32_16x16x32_bf16 v[96:99], v[182:185], v[202:205], v[96:99]
	v_mfma_f32_16x16x32_bf16 v[84:87], v[174:177], v[210:213], v[84:87]
	v_mfma_f32_16x16x32_bf16 v[80:83], v[182:185], v[210:213], v[80:83]
	v_mfma_f32_16x16x32_bf16 v[68:71], v[174:177], v[218:221], v[68:71]
	v_mfma_f32_16x16x32_bf16 v[64:67], v[182:185], v[218:221], v[64:67]
	v_mfma_f32_16x16x32_bf16 v[116:119], v[178:181], v[198:201], v[116:119]
	v_mfma_f32_16x16x32_bf16 v[112:115], v[186:189], v[198:201], v[112:115]
	v_mfma_f32_16x16x32_bf16 v[100:103], v[178:181], v[206:209], v[100:103]
	v_mfma_f32_16x16x32_bf16 v[96:99], v[186:189], v[206:209], v[96:99]
	v_mfma_f32_16x16x32_bf16 v[84:87], v[178:181], v[214:217], v[84:87]
	v_mfma_f32_16x16x32_bf16 v[80:83], v[186:189], v[214:217], v[80:83]
	v_mfma_f32_16x16x32_bf16 v[68:71], v[178:181], v[222:225], v[68:71]
	v_mfma_f32_16x16x32_bf16 v[64:67], v[186:189], v[222:225], v[64:67]
	s_setprio 0
	s_barrier
	s_add_i32 s66, s55, s3
	v_lshl_add_u64 v[156:157], s[8:9], 0, v[130:131]
	s_mov_b32 m0, s66
	ds_read_b128 v[190:193], v155 offset:16384
	ds_read_b128 v[198:201], v155 offset:17408
	ds_read_b128 v[202:205], v155 offset:18432
	ds_read_b128 v[206:209], v155 offset:19456
	ds_read_b128 v[210:213], v155 offset:20480
	ds_read_b128 v[214:217], v155 offset:21504
	ds_read_b128 v[218:221], v155 offset:22528
	ds_read_b128 v[222:225], v155 offset:23552
	global_load_lds_dwordx4 v[156:157], off
	s_add_i32 m0, s66, 0x2000
	s_add_u32 s66, s8, 0x40000
	v_lshl_add_u64 v[226:227], s[8:9], 0, v[134:135]
	s_addc_u32 s67, s9, 0
	s_add_i32 s73, s58, s3
	global_load_lds_dwordx4 v[226:227], off
	v_lshl_add_u64 v[228:229], s[66:67], 0, v[130:131]
	s_mov_b32 m0, s73
	v_lshl_add_u64 v[230:231], s[40:41], 0, v[132:133]
	global_load_lds_dwordx4 v[228:229], off
	v_lshl_add_u64 v[228:229], s[66:67], 0, v[134:135]
	s_add_i32 m0, s73, 0x2000
	s_nop 0
	global_load_lds_dwordx4 v[228:229], off
	s_waitcnt vmcnt(6)
	s_waitcnt lgkmcnt(0)
	s_barrier
	s_setprio 1
	s_waitcnt lgkmcnt(0)
	v_mfma_f32_16x16x32_bf16 v[60:63], v[144:147], v[190:193], v[60:63]
	v_mfma_f32_16x16x32_bf16 v[56:59], v[166:169], v[190:193], v[56:59]
	v_mfma_f32_16x16x32_bf16 v[44:47], v[144:147], v[202:205], v[44:47]
	v_mfma_f32_16x16x32_bf16 v[40:43], v[166:169], v[202:205], v[40:43]
	v_mfma_f32_16x16x32_bf16 v[28:31], v[144:147], v[210:213], v[28:31]
	v_mfma_f32_16x16x32_bf16 v[24:27], v[166:169], v[210:213], v[24:27]
	v_mfma_f32_16x16x32_bf16 v[12:15], v[144:147], v[218:221], v[12:15]
	v_mfma_f32_16x16x32_bf16 v[8:11], v[166:169], v[218:221], v[8:11]
	v_mfma_f32_16x16x32_bf16 v[60:63], v[162:165], v[198:201], v[60:63]
	v_mfma_f32_16x16x32_bf16 v[56:59], v[170:173], v[198:201], v[56:59]
	v_mfma_f32_16x16x32_bf16 v[44:47], v[162:165], v[206:209], v[44:47]
	v_mfma_f32_16x16x32_bf16 v[40:43], v[170:173], v[206:209], v[40:43]
	v_mfma_f32_16x16x32_bf16 v[28:31], v[162:165], v[214:217], v[28:31]
	v_mfma_f32_16x16x32_bf16 v[24:27], v[170:173], v[214:217], v[24:27]
	v_mfma_f32_16x16x32_bf16 v[12:15], v[162:165], v[222:225], v[12:15]
	v_mfma_f32_16x16x32_bf16 v[8:11], v[170:173], v[222:225], v[8:11]
	s_setprio 0
	s_setprio 1
	v_mfma_f32_16x16x32_bf16 v[52:55], v[174:177], v[190:193], v[52:55]
	v_mfma_f32_16x16x32_bf16 v[48:51], v[182:185], v[190:193], v[48:51]
	v_mfma_f32_16x16x32_bf16 v[36:39], v[174:177], v[202:205], v[36:39]
	v_mfma_f32_16x16x32_bf16 v[32:35], v[182:185], v[202:205], v[32:35]
	v_mfma_f32_16x16x32_bf16 v[20:23], v[174:177], v[210:213], v[20:23]
	v_mfma_f32_16x16x32_bf16 v[16:19], v[182:185], v[210:213], v[16:19]
	v_mfma_f32_16x16x32_bf16 v[4:7], v[174:177], v[218:221], v[4:7]
	v_mfma_f32_16x16x32_bf16 v[0:3], v[182:185], v[218:221], v[0:3]
	v_mfma_f32_16x16x32_bf16 v[52:55], v[178:181], v[198:201], v[52:55]
	v_mfma_f32_16x16x32_bf16 v[48:51], v[186:189], v[198:201], v[48:51]
	v_mfma_f32_16x16x32_bf16 v[36:39], v[178:181], v[206:209], v[36:39]
	v_mfma_f32_16x16x32_bf16 v[32:35], v[186:189], v[206:209], v[32:35]
	v_mfma_f32_16x16x32_bf16 v[20:23], v[178:181], v[214:217], v[20:23]
	v_mfma_f32_16x16x32_bf16 v[16:19], v[186:189], v[214:217], v[16:19]
	v_mfma_f32_16x16x32_bf16 v[4:7], v[178:181], v[222:225], v[4:7]
	v_mfma_f32_16x16x32_bf16 v[0:3], v[186:189], v[222:225], v[0:3]
	s_setprio 0
	s_barrier
	v_lshl_add_u64 v[228:229], s[40:41], 0, v[128:129]
	s_mov_b32 m0, s4
	s_nop 0
	global_load_lds_dwordx4 v[228:229], off
	s_mov_b32 m0, s5
	s_nop 0
	global_load_lds_dwordx4 v[230:231], off
	s_add_i32 s66, 0, 0x18000
	v_add_u32_e32 v158, s66, v149
	s_add_i32 s67, 0, 0x1c000
	ds_read_b128 v[144:147], v158
	ds_read_b128 v[162:165], v158 offset:1024
	ds_read_b128 v[166:169], v158 offset:2048
	ds_read_b128 v[170:173], v158 offset:3072
	v_add_u32_e32 v158, s67, v149
	ds_read_b128 v[174:177], v158
	ds_read_b128 v[178:181], v158 offset:1024
	ds_read_b128 v[182:185], v158 offset:2048
	ds_read_b128 v[186:189], v158 offset:3072
	s_add_u32 s40, s40, 0x40000
	s_addc_u32 s41, s41, 0
	s_mov_b32 m0, s16
	v_lshl_add_u64 v[232:233], s[40:41], 0, v[128:129]
	ds_read_b128 v[190:193], v155 offset:32768
	ds_read_b128 v[198:201], v155 offset:33792
	ds_read_b128 v[202:205], v155 offset:34816
	ds_read_b128 v[206:209], v155 offset:35840
	ds_read_b128 v[210:213], v155 offset:36864
	ds_read_b128 v[214:217], v155 offset:37888
	ds_read_b128 v[218:221], v155 offset:38912
	ds_read_b128 v[222:225], v155 offset:39936
	global_load_lds_dwordx4 v[232:233], off
	v_lshl_add_u64 v[232:233], s[40:41], 0, v[132:133]
	s_mov_b32 m0, s17
	s_nop 0
	global_load_lds_dwordx4 v[232:233], off
	s_waitcnt vmcnt(8)
	s_waitcnt lgkmcnt(0)
	s_barrier
	s_setprio 1
	s_waitcnt lgkmcnt(0)
	v_mfma_f32_16x16x32_bf16 v[124:127], v[144:147], v[190:193], v[124:127]
	v_mfma_f32_16x16x32_bf16 v[120:123], v[166:169], v[190:193], v[120:123]
	v_mfma_f32_16x16x32_bf16 v[108:111], v[144:147], v[202:205], v[108:111]
	v_mfma_f32_16x16x32_bf16 v[104:107], v[166:169], v[202:205], v[104:107]
	v_mfma_f32_16x16x32_bf16 v[92:95], v[144:147], v[210:213], v[92:95]
	v_mfma_f32_16x16x32_bf16 v[88:91], v[166:169], v[210:213], v[88:91]
	v_mfma_f32_16x16x32_bf16 v[76:79], v[144:147], v[218:221], v[76:79]
	v_mfma_f32_16x16x32_bf16 v[72:75], v[166:169], v[218:221], v[72:75]
	v_mfma_f32_16x16x32_bf16 v[124:127], v[162:165], v[198:201], v[124:127]
	v_mfma_f32_16x16x32_bf16 v[120:123], v[170:173], v[198:201], v[120:123]
	v_mfma_f32_16x16x32_bf16 v[108:111], v[162:165], v[206:209], v[108:111]
	v_mfma_f32_16x16x32_bf16 v[104:107], v[170:173], v[206:209], v[104:107]
	v_mfma_f32_16x16x32_bf16 v[92:95], v[162:165], v[214:217], v[92:95]
	v_mfma_f32_16x16x32_bf16 v[88:91], v[170:173], v[214:217], v[88:91]
	v_mfma_f32_16x16x32_bf16 v[76:79], v[162:165], v[222:225], v[76:79]
	v_mfma_f32_16x16x32_bf16 v[72:75], v[170:173], v[222:225], v[72:75]
	s_setprio 0
	s_setprio 1
	v_mfma_f32_16x16x32_bf16 v[116:119], v[174:177], v[190:193], v[116:119]
	v_mfma_f32_16x16x32_bf16 v[112:115], v[182:185], v[190:193], v[112:115]
	v_mfma_f32_16x16x32_bf16 v[100:103], v[174:177], v[202:205], v[100:103]
	v_mfma_f32_16x16x32_bf16 v[96:99], v[182:185], v[202:205], v[96:99]
	v_mfma_f32_16x16x32_bf16 v[84:87], v[174:177], v[210:213], v[84:87]
	v_mfma_f32_16x16x32_bf16 v[80:83], v[182:185], v[210:213], v[80:83]
	v_mfma_f32_16x16x32_bf16 v[68:71], v[174:177], v[218:221], v[68:71]
	v_mfma_f32_16x16x32_bf16 v[64:67], v[182:185], v[218:221], v[64:67]
	v_mfma_f32_16x16x32_bf16 v[116:119], v[178:181], v[198:201], v[116:119]
	v_mfma_f32_16x16x32_bf16 v[112:115], v[186:189], v[198:201], v[112:115]
	v_mfma_f32_16x16x32_bf16 v[100:103], v[178:181], v[206:209], v[100:103]
	v_mfma_f32_16x16x32_bf16 v[96:99], v[186:189], v[206:209], v[96:99]
	v_mfma_f32_16x16x32_bf16 v[84:87], v[178:181], v[214:217], v[84:87]
	v_mfma_f32_16x16x32_bf16 v[80:83], v[186:189], v[214:217], v[80:83]
	v_mfma_f32_16x16x32_bf16 v[68:71], v[178:181], v[222:225], v[68:71]
	v_mfma_f32_16x16x32_bf16 v[64:67], v[186:189], v[222:225], v[64:67]
	s_setprio 0
	s_barrier
	s_add_i32 s40, s66, s3
	v_lshl_add_u64 v[156:157], v[156:157], 0, s[12:13]
	s_mov_b32 m0, s40
	ds_read_b128 v[190:193], v155 offset:49152
	ds_read_b128 v[198:201], v155 offset:50176
	ds_read_b128 v[202:205], v155 offset:51200
	ds_read_b128 v[206:209], v155 offset:52224
	ds_read_b128 v[210:213], v155 offset:53248
	ds_read_b128 v[214:217], v155 offset:54272
	ds_read_b128 v[218:221], v155 offset:55296
	ds_read_b128 v[222:225], v155 offset:56320
	global_load_lds_dwordx4 v[156:157], off
	s_add_i32 m0, s40, 0x2000
	s_add_u32 s8, s8, 0x40080
	v_lshl_add_u64 v[156:157], v[226:227], 0, s[12:13]
	s_addc_u32 s9, s9, 0
	s_add_i32 s40, s67, s3
	global_load_lds_dwordx4 v[156:157], off
	v_lshl_add_u64 v[156:157], s[8:9], 0, v[130:131]
	s_mov_b32 m0, s40
	s_nop 0
	global_load_lds_dwordx4 v[156:157], off
	v_lshl_add_u64 v[156:157], s[8:9], 0, v[134:135]
	s_add_i32 m0, s40, 0x2000
	s_nop 0
	global_load_lds_dwordx4 v[156:157], off
	v_lshl_add_u64 v[156:157], v[228:229], 0, s[12:13]
	s_mov_b32 m0, s19
	s_nop 0
	global_load_lds_dwordx4 v[156:157], off
	v_lshl_add_u64 v[156:157], v[230:231], 0, s[12:13]
	s_mov_b32 m0, s33
	s_nop 0
	global_load_lds_dwordx4 v[156:157], off
	s_waitcnt vmcnt(8)
	s_waitcnt lgkmcnt(0)
	s_barrier
	s_setprio 1
	s_waitcnt lgkmcnt(0)
	v_mfma_f32_16x16x32_bf16 v[60:63], v[144:147], v[190:193], v[60:63]
	v_mfma_f32_16x16x32_bf16 v[56:59], v[166:169], v[190:193], v[56:59]
	v_mfma_f32_16x16x32_bf16 v[44:47], v[144:147], v[202:205], v[44:47]
	v_mfma_f32_16x16x32_bf16 v[40:43], v[166:169], v[202:205], v[40:43]
	v_mfma_f32_16x16x32_bf16 v[28:31], v[144:147], v[210:213], v[28:31]
	v_mfma_f32_16x16x32_bf16 v[24:27], v[166:169], v[210:213], v[24:27]
	v_mfma_f32_16x16x32_bf16 v[12:15], v[144:147], v[218:221], v[12:15]
	v_mfma_f32_16x16x32_bf16 v[8:11], v[166:169], v[218:221], v[8:11]
	v_mfma_f32_16x16x32_bf16 v[60:63], v[162:165], v[198:201], v[60:63]
	v_mfma_f32_16x16x32_bf16 v[56:59], v[170:173], v[198:201], v[56:59]
	v_mfma_f32_16x16x32_bf16 v[44:47], v[162:165], v[206:209], v[44:47]
	v_mfma_f32_16x16x32_bf16 v[40:43], v[170:173], v[206:209], v[40:43]
	v_mfma_f32_16x16x32_bf16 v[28:31], v[162:165], v[214:217], v[28:31]
	v_mfma_f32_16x16x32_bf16 v[24:27], v[170:173], v[214:217], v[24:27]
	v_mfma_f32_16x16x32_bf16 v[12:15], v[162:165], v[222:225], v[12:15]
	v_mfma_f32_16x16x32_bf16 v[8:11], v[170:173], v[222:225], v[8:11]
	s_setprio 0
	s_setprio 1
	v_mfma_f32_16x16x32_bf16 v[52:55], v[174:177], v[190:193], v[52:55]
	v_mfma_f32_16x16x32_bf16 v[48:51], v[182:185], v[190:193], v[48:51]
	v_mfma_f32_16x16x32_bf16 v[36:39], v[174:177], v[202:205], v[36:39]
	v_mfma_f32_16x16x32_bf16 v[32:35], v[182:185], v[202:205], v[32:35]
	v_mfma_f32_16x16x32_bf16 v[20:23], v[174:177], v[210:213], v[20:23]
	v_mfma_f32_16x16x32_bf16 v[16:19], v[182:185], v[210:213], v[16:19]
	v_mfma_f32_16x16x32_bf16 v[4:7], v[174:177], v[218:221], v[4:7]
	v_mfma_f32_16x16x32_bf16 v[0:3], v[182:185], v[218:221], v[0:3]
	v_mfma_f32_16x16x32_bf16 v[52:55], v[178:181], v[198:201], v[52:55]
	v_mfma_f32_16x16x32_bf16 v[48:51], v[186:189], v[198:201], v[48:51]
	v_mfma_f32_16x16x32_bf16 v[36:39], v[178:181], v[206:209], v[36:39]
	v_mfma_f32_16x16x32_bf16 v[32:35], v[186:189], v[206:209], v[32:35]
	v_mfma_f32_16x16x32_bf16 v[20:23], v[178:181], v[214:217], v[20:23]
	v_mfma_f32_16x16x32_bf16 v[16:19], v[186:189], v[214:217], v[16:19]
	v_mfma_f32_16x16x32_bf16 v[4:7], v[178:181], v[222:225], v[4:7]
	v_mfma_f32_16x16x32_bf16 v[0:3], v[186:189], v[222:225], v[0:3]
	s_setprio 0
	s_barrier
	s_add_i32 s65, s65, 2
	s_add_u32 s38, s38, 0x100
	s_addc_u32 s39, s39, 0
	s_add_u32 s61, s61, 0x100
	s_addc_u32 s64, s64, 0
	s_cmp_gt_u32 s65, 13
	s_cbranch_scc0 .LBB0_666
	s_and_b64 vcc, exec, s[14:15]
	s_cbranch_vccz .LBB0_669
	s_barrier

.LBB0_765:
	ds_read_b128 v[144:147], v154
	ds_read_b128 v[162:165], v154 offset:1024
	ds_read_b128 v[166:169], v154 offset:2048
	ds_read_b128 v[170:173], v154 offset:3072
	ds_read_b128 v[174:177], v155
	ds_read_b128 v[178:181], v155 offset:1024
	ds_read_b128 v[182:185], v155 offset:2048
	ds_read_b128 v[186:189], v155 offset:3072
	s_add_u32 s8, s30, 0xfffc0080
	s_addc_u32 s9, s31, -1
	s_cmp_eq_u32 s60, 12
	s_cselect_b32 s37, s15, s9
	s_cselect_b32 s36, s47, s8
	s_cselect_b32 s9, s13, s59
	s_cselect_b32 s8, s55, s58
	v_lshl_add_u64 v[148:149], s[30:31], 0, v[136:137]
	s_add_i32 m0, s4, 0xc000
	ds_read_b128 v[190:193], v156
	ds_read_b128 v[198:201], v156 offset:1024
	ds_read_b128 v[202:205], v156 offset:2048
	ds_read_b128 v[206:209], v156 offset:3072
	ds_read_b128 v[210:213], v156 offset:4096
	ds_read_b128 v[214:217], v156 offset:5120
	ds_read_b128 v[218:221], v156 offset:6144
	ds_read_b128 v[222:225], v156 offset:7168
	global_load_lds_dwordx4 v[148:149], off
	v_lshl_add_u64 v[148:149], s[30:31], 0, v[138:139]
	s_add_i32 m0, s4, 0xe000
	s_nop 0
	global_load_lds_dwordx4 v[148:149], off
	s_waitcnt vmcnt(8)
	s_waitcnt lgkmcnt(0)
	s_barrier
	s_setprio 1
	s_waitcnt lgkmcnt(0)
	v_mfma_f32_16x16x32_bf16 v[124:127], v[144:147], v[190:193], v[124:127]
	v_mfma_f32_16x16x32_bf16 v[120:123], v[166:169], v[190:193], v[120:123]
	v_mfma_f32_16x16x32_bf16 v[108:111], v[144:147], v[202:205], v[108:111]
	v_mfma_f32_16x16x32_bf16 v[104:107], v[166:169], v[202:205], v[104:107]
	v_mfma_f32_16x16x32_bf16 v[92:95], v[144:147], v[210:213], v[92:95]
	v_mfma_f32_16x16x32_bf16 v[88:91], v[166:169], v[210:213], v[88:91]
	v_mfma_f32_16x16x32_bf16 v[76:79], v[144:147], v[218:221], v[76:79]
	v_mfma_f32_16x16x32_bf16 v[72:75], v[166:169], v[218:221], v[72:75]
	v_mfma_f32_16x16x32_bf16 v[124:127], v[162:165], v[198:201], v[124:127]
	v_mfma_f32_16x16x32_bf16 v[120:123], v[170:173], v[198:201], v[120:123]
	v_mfma_f32_16x16x32_bf16 v[108:111], v[162:165], v[206:209], v[108:111]
	v_mfma_f32_16x16x32_bf16 v[104:107], v[170:173], v[206:209], v[104:107]
	v_mfma_f32_16x16x32_bf16 v[92:95], v[162:165], v[214:217], v[92:95]
	v_mfma_f32_16x16x32_bf16 v[88:91], v[170:173], v[214:217], v[88:91]
	v_mfma_f32_16x16x32_bf16 v[76:79], v[162:165], v[222:225], v[76:79]
	v_mfma_f32_16x16x32_bf16 v[72:75], v[170:173], v[222:225], v[72:75]
	s_setprio 0
	s_setprio 1
	v_mfma_f32_16x16x32_bf16 v[116:119], v[174:177], v[190:193], v[116:119]
	v_mfma_f32_16x16x32_bf16 v[112:115], v[182:185], v[190:193], v[112:115]
	v_mfma_f32_16x16x32_bf16 v[100:103], v[174:177], v[202:205], v[100:103]
	v_mfma_f32_16x16x32_bf16 v[96:99], v[182:185], v[202:205], v[96:99]
	v_mfma_f32_16x16x32_bf16 v[84:87], v[174:177], v[210:213], v[84:87]
	v_mfma_f32_16x16x32_bf16 v[80:83], v[182:185], v[210:213], v[80:83]
	v_mfma_f32_16x16x32_bf16 v[68:71], v[174:177], v[218:221], v[68:71]
	v_mfma_f32_16x16x32_bf16 v[64:67], v[182:185], v[218:221], v[64:67]
	v_mfma_f32_16x16x32_bf16 v[116:119], v[178:181], v[198:201], v[116:119]
	v_mfma_f32_16x16x32_bf16 v[112:115], v[186:189], v[198:201], v[112:115]
	v_mfma_f32_16x16x32_bf16 v[100:103], v[178:181], v[206:209], v[100:103]
	v_mfma_f32_16x16x32_bf16 v[96:99], v[186:189], v[206:209], v[96:99]
	v_mfma_f32_16x16x32_bf16 v[84:87], v[178:181], v[214:217], v[84:87]
	v_mfma_f32_16x16x32_bf16 v[80:83], v[186:189], v[214:217], v[80:83]
	v_mfma_f32_16x16x32_bf16 v[68:71], v[178:181], v[222:225], v[68:71]
	v_mfma_f32_16x16x32_bf16 v[64:67], v[186:189], v[222:225], v[64:67]
	s_setprio 0
	s_barrier
	s_add_i32 s61, s38, s3
	v_lshl_add_u64 v[148:149], s[8:9], 0, v[132:133]
	s_mov_b32 m0, s61
	ds_read_b128 v[190:193], v156 offset:16384
	ds_read_b128 v[198:201], v156 offset:17408
	ds_read_b128 v[202:205], v156 offset:18432
	ds_read_b128 v[206:209], v156 offset:19456
	ds_read_b128 v[210:213], v156 offset:20480
	ds_read_b128 v[214:217], v156 offset:21504
	ds_read_b128 v[218:221], v156 offset:22528
	ds_read_b128 v[222:225], v156 offset:23552
	global_load_lds_dwordx4 v[148:149], off
	s_add_i32 m0, s61, 0x2000
	s_add_u32 s64, s8, 0x40000
	v_lshl_add_u64 v[226:227], s[8:9], 0, v[128:129]
	s_addc_u32 s65, s9, 0
	s_add_i32 s61, s39, s3
	global_load_lds_dwordx4 v[226:227], off
	v_lshl_add_u64 v[228:229], s[64:65], 0, v[132:133]
	s_mov_b32 m0, s61
	v_lshl_add_u64 v[230:231], s[36:37], 0, v[130:131]
	global_load_lds_dwordx4 v[228:229], off
	v_lshl_add_u64 v[228:229], s[64:65], 0, v[128:129]
	s_add_i32 m0, s61, 0x2000
	s_nop 0
	global_load_lds_dwordx4 v[228:229], off
	s_waitcnt vmcnt(6)
	s_waitcnt lgkmcnt(0)
	s_barrier
	s_setprio 1
	s_waitcnt lgkmcnt(0)
	v_mfma_f32_16x16x32_bf16 v[60:63], v[144:147], v[190:193], v[60:63]
	v_mfma_f32_16x16x32_bf16 v[56:59], v[166:169], v[190:193], v[56:59]
	v_mfma_f32_16x16x32_bf16 v[44:47], v[144:147], v[202:205], v[44:47]
	v_mfma_f32_16x16x32_bf16 v[40:43], v[166:169], v[202:205], v[40:43]
	v_mfma_f32_16x16x32_bf16 v[28:31], v[144:147], v[210:213], v[28:31]
	v_mfma_f32_16x16x32_bf16 v[24:27], v[166:169], v[210:213], v[24:27]
	v_mfma_f32_16x16x32_bf16 v[12:15], v[144:147], v[218:221], v[12:15]
	v_mfma_f32_16x16x32_bf16 v[8:11], v[166:169], v[218:221], v[8:11]
	v_mfma_f32_16x16x32_bf16 v[60:63], v[162:165], v[198:201], v[60:63]
	v_mfma_f32_16x16x32_bf16 v[56:59], v[170:173], v[198:201], v[56:59]
	v_mfma_f32_16x16x32_bf16 v[44:47], v[162:165], v[206:209], v[44:47]
	v_mfma_f32_16x16x32_bf16 v[40:43], v[170:173], v[206:209], v[40:43]
	v_mfma_f32_16x16x32_bf16 v[28:31], v[162:165], v[214:217], v[28:31]
	v_mfma_f32_16x16x32_bf16 v[24:27], v[170:173], v[214:217], v[24:27]
	v_mfma_f32_16x16x32_bf16 v[12:15], v[162:165], v[222:225], v[12:15]
	v_mfma_f32_16x16x32_bf16 v[8:11], v[170:173], v[222:225], v[8:11]
	s_setprio 0
	s_setprio 1
	v_mfma_f32_16x16x32_bf16 v[52:55], v[174:177], v[190:193], v[52:55]
	v_mfma_f32_16x16x32_bf16 v[48:51], v[182:185], v[190:193], v[48:51]
	v_mfma_f32_16x16x32_bf16 v[36:39], v[174:177], v[202:205], v[36:39]
	v_mfma_f32_16x16x32_bf16 v[32:35], v[182:185], v[202:205], v[32:35]
	v_mfma_f32_16x16x32_bf16 v[20:23], v[174:177], v[210:213], v[20:23]
	v_mfma_f32_16x16x32_bf16 v[16:19], v[182:185], v[210:213], v[16:19]
	v_mfma_f32_16x16x32_bf16 v[4:7], v[174:177], v[218:221], v[4:7]
	v_mfma_f32_16x16x32_bf16 v[0:3], v[182:185], v[218:221], v[0:3]
	v_mfma_f32_16x16x32_bf16 v[52:55], v[178:181], v[198:201], v[52:55]
	v_mfma_f32_16x16x32_bf16 v[48:51], v[186:189], v[198:201], v[48:51]
	v_mfma_f32_16x16x32_bf16 v[36:39], v[178:181], v[206:209], v[36:39]
	v_mfma_f32_16x16x32_bf16 v[32:35], v[186:189], v[206:209], v[32:35]
	v_mfma_f32_16x16x32_bf16 v[20:23], v[178:181], v[214:217], v[20:23]
	v_mfma_f32_16x16x32_bf16 v[16:19], v[186:189], v[214:217], v[16:19]
	v_mfma_f32_16x16x32_bf16 v[4:7], v[178:181], v[222:225], v[4:7]
	v_mfma_f32_16x16x32_bf16 v[0:3], v[186:189], v[222:225], v[0:3]
	s_setprio 0
	s_barrier
	v_lshl_add_u64 v[228:229], s[36:37], 0, v[134:135]
	s_mov_b32 m0, s4
	s_nop 0
	global_load_lds_dwordx4 v[228:229], off
	s_mov_b32 m0, s5
	s_nop 0
	global_load_lds_dwordx4 v[230:231], off
	s_add_i32 s61, 0, 0x18000
	v_add_u32_e32 v157, s61, v151
	s_add_i32 s64, 0, 0x1c000
	ds_read_b128 v[144:147], v157
	ds_read_b128 v[162:165], v157 offset:1024
	ds_read_b128 v[166:169], v157 offset:2048
	ds_read_b128 v[170:173], v157 offset:3072
	v_add_u32_e32 v157, s64, v151
	ds_read_b128 v[174:177], v157
	ds_read_b128 v[178:181], v157 offset:1024
	ds_read_b128 v[182:185], v157 offset:2048
	ds_read_b128 v[186:189], v157 offset:3072
	s_add_u32 s36, s36, 0x40000
	s_addc_u32 s37, s37, 0
	s_mov_b32 m0, s16
	v_lshl_add_u64 v[232:233], s[36:37], 0, v[134:135]
	ds_read_b128 v[190:193], v156 offset:32768
	ds_read_b128 v[198:201], v156 offset:33792
	ds_read_b128 v[202:205], v156 offset:34816
	ds_read_b128 v[206:209], v156 offset:35840
	ds_read_b128 v[210:213], v156 offset:36864
	ds_read_b128 v[214:217], v156 offset:37888
	ds_read_b128 v[218:221], v156 offset:38912
	ds_read_b128 v[222:225], v156 offset:39936
	global_load_lds_dwordx4 v[232:233], off
	v_lshl_add_u64 v[232:233], s[36:37], 0, v[130:131]
	s_mov_b32 m0, s17
	s_nop 0
	global_load_lds_dwordx4 v[232:233], off
	s_waitcnt vmcnt(8)
	s_waitcnt lgkmcnt(0)
	s_barrier
	s_setprio 1
	s_waitcnt lgkmcnt(0)
	v_mfma_f32_16x16x32_bf16 v[124:127], v[144:147], v[190:193], v[124:127]
	v_mfma_f32_16x16x32_bf16 v[120:123], v[166:169], v[190:193], v[120:123]
	v_mfma_f32_16x16x32_bf16 v[108:111], v[144:147], v[202:205], v[108:111]
	v_mfma_f32_16x16x32_bf16 v[104:107], v[166:169], v[202:205], v[104:107]
	v_mfma_f32_16x16x32_bf16 v[92:95], v[144:147], v[210:213], v[92:95]
	v_mfma_f32_16x16x32_bf16 v[88:91], v[166:169], v[210:213], v[88:91]
	v_mfma_f32_16x16x32_bf16 v[76:79], v[144:147], v[218:221], v[76:79]
	v_mfma_f32_16x16x32_bf16 v[72:75], v[166:169], v[218:221], v[72:75]
	v_mfma_f32_16x16x32_bf16 v[124:127], v[162:165], v[198:201], v[124:127]
	v_mfma_f32_16x16x32_bf16 v[120:123], v[170:173], v[198:201], v[120:123]
	v_mfma_f32_16x16x32_bf16 v[108:111], v[162:165], v[206:209], v[108:111]
	v_mfma_f32_16x16x32_bf16 v[104:107], v[170:173], v[206:209], v[104:107]
	v_mfma_f32_16x16x32_bf16 v[92:95], v[162:165], v[214:217], v[92:95]
	v_mfma_f32_16x16x32_bf16 v[88:91], v[170:173], v[214:217], v[88:91]
	v_mfma_f32_16x16x32_bf16 v[76:79], v[162:165], v[222:225], v[76:79]
	v_mfma_f32_16x16x32_bf16 v[72:75], v[170:173], v[222:225], v[72:75]
	s_setprio 0
	s_setprio 1
	v_mfma_f32_16x16x32_bf16 v[116:119], v[174:177], v[190:193], v[116:119]
	v_mfma_f32_16x16x32_bf16 v[112:115], v[182:185], v[190:193], v[112:115]
	v_mfma_f32_16x16x32_bf16 v[100:103], v[174:177], v[202:205], v[100:103]
	v_mfma_f32_16x16x32_bf16 v[96:99], v[182:185], v[202:205], v[96:99]
	v_mfma_f32_16x16x32_bf16 v[84:87], v[174:177], v[210:213], v[84:87]
	v_mfma_f32_16x16x32_bf16 v[80:83], v[182:185], v[210:213], v[80:83]
	v_mfma_f32_16x16x32_bf16 v[68:71], v[174:177], v[218:221], v[68:71]
	v_mfma_f32_16x16x32_bf16 v[64:67], v[182:185], v[218:221], v[64:67]
	v_mfma_f32_16x16x32_bf16 v[116:119], v[178:181], v[198:201], v[116:119]
	v_mfma_f32_16x16x32_bf16 v[112:115], v[186:189], v[198:201], v[112:115]
	v_mfma_f32_16x16x32_bf16 v[100:103], v[178:181], v[206:209], v[100:103]
	v_mfma_f32_16x16x32_bf16 v[96:99], v[186:189], v[206:209], v[96:99]
	v_mfma_f32_16x16x32_bf16 v[84:87], v[178:181], v[214:217], v[84:87]
	v_mfma_f32_16x16x32_bf16 v[80:83], v[186:189], v[214:217], v[80:83]
	v_mfma_f32_16x16x32_bf16 v[68:71], v[178:181], v[222:225], v[68:71]
	v_mfma_f32_16x16x32_bf16 v[64:67], v[186:189], v[222:225], v[64:67]
	s_setprio 0
	s_barrier
	s_add_i32 s36, s61, s3
	v_lshl_add_u64 v[148:149], v[148:149], 0, s[6:7]
	s_mov_b32 m0, s36
	ds_read_b128 v[190:193], v156 offset:49152
	ds_read_b128 v[198:201], v156 offset:50176
	ds_read_b128 v[202:205], v156 offset:51200
	ds_read_b128 v[206:209], v156 offset:52224
	ds_read_b128 v[210:213], v156 offset:53248
	ds_read_b128 v[214:217], v156 offset:54272
	ds_read_b128 v[218:221], v156 offset:55296
	ds_read_b128 v[222:225], v156 offset:56320
	global_load_lds_dwordx4 v[148:149], off
	s_add_i32 m0, s36, 0x2000
	s_add_u32 s8, s8, 0x40080
	v_lshl_add_u64 v[148:149], v[226:227], 0, s[6:7]
	s_addc_u32 s9, s9, 0
	s_add_i32 s36, s64, s3
	global_load_lds_dwordx4 v[148:149], off
	v_lshl_add_u64 v[148:149], s[8:9], 0, v[132:133]
	s_mov_b32 m0, s36
	s_nop 0
	global_load_lds_dwordx4 v[148:149], off
	v_lshl_add_u64 v[148:149], s[8:9], 0, v[128:129]
	s_add_i32 m0, s36, 0x2000
	s_nop 0
	global_load_lds_dwordx4 v[148:149], off
	v_lshl_add_u64 v[148:149], v[228:229], 0, s[6:7]
	s_mov_b32 m0, s29
	s_nop 0
	global_load_lds_dwordx4 v[148:149], off
	v_lshl_add_u64 v[148:149], v[230:231], 0, s[6:7]
	s_mov_b32 m0, s33
	s_nop 0
	global_load_lds_dwordx4 v[148:149], off
	s_waitcnt vmcnt(8)
	s_waitcnt lgkmcnt(0)
	s_barrier
	s_setprio 1
	s_waitcnt lgkmcnt(0)
	v_mfma_f32_16x16x32_bf16 v[60:63], v[144:147], v[190:193], v[60:63]
	v_mfma_f32_16x16x32_bf16 v[56:59], v[166:169], v[190:193], v[56:59]
	v_mfma_f32_16x16x32_bf16 v[44:47], v[144:147], v[202:205], v[44:47]
	v_mfma_f32_16x16x32_bf16 v[40:43], v[166:169], v[202:205], v[40:43]
	v_mfma_f32_16x16x32_bf16 v[28:31], v[144:147], v[210:213], v[28:31]
	v_mfma_f32_16x16x32_bf16 v[24:27], v[166:169], v[210:213], v[24:27]
	v_mfma_f32_16x16x32_bf16 v[12:15], v[144:147], v[218:221], v[12:15]
	v_mfma_f32_16x16x32_bf16 v[8:11], v[166:169], v[218:221], v[8:11]
	v_mfma_f32_16x16x32_bf16 v[60:63], v[162:165], v[198:201], v[60:63]
	v_mfma_f32_16x16x32_bf16 v[56:59], v[170:173], v[198:201], v[56:59]
	v_mfma_f32_16x16x32_bf16 v[44:47], v[162:165], v[206:209], v[44:47]
	v_mfma_f32_16x16x32_bf16 v[40:43], v[170:173], v[206:209], v[40:43]
	v_mfma_f32_16x16x32_bf16 v[28:31], v[162:165], v[214:217], v[28:31]
	v_mfma_f32_16x16x32_bf16 v[24:27], v[170:173], v[214:217], v[24:27]
	v_mfma_f32_16x16x32_bf16 v[12:15], v[162:165], v[222:225], v[12:15]
	v_mfma_f32_16x16x32_bf16 v[8:11], v[170:173], v[222:225], v[8:11]
	s_setprio 0
	s_setprio 1
	v_mfma_f32_16x16x32_bf16 v[52:55], v[174:177], v[190:193], v[52:55]
	v_mfma_f32_16x16x32_bf16 v[48:51], v[182:185], v[190:193], v[48:51]
	v_mfma_f32_16x16x32_bf16 v[36:39], v[174:177], v[202:205], v[36:39]
	v_mfma_f32_16x16x32_bf16 v[32:35], v[182:185], v[202:205], v[32:35]
	v_mfma_f32_16x16x32_bf16 v[20:23], v[174:177], v[210:213], v[20:23]
	v_mfma_f32_16x16x32_bf16 v[16:19], v[182:185], v[210:213], v[16:19]
	v_mfma_f32_16x16x32_bf16 v[4:7], v[174:177], v[218:221], v[4:7]
	v_mfma_f32_16x16x32_bf16 v[0:3], v[182:185], v[218:221], v[0:3]
	v_mfma_f32_16x16x32_bf16 v[52:55], v[178:181], v[198:201], v[52:55]
	v_mfma_f32_16x16x32_bf16 v[48:51], v[186:189], v[198:201], v[48:51]
	v_mfma_f32_16x16x32_bf16 v[36:39], v[178:181], v[206:209], v[36:39]
	v_mfma_f32_16x16x32_bf16 v[32:35], v[186:189], v[206:209], v[32:35]
	v_mfma_f32_16x16x32_bf16 v[20:23], v[178:181], v[214:217], v[20:23]
	v_mfma_f32_16x16x32_bf16 v[16:19], v[186:189], v[214:217], v[16:19]
	v_mfma_f32_16x16x32_bf16 v[4:7], v[178:181], v[222:225], v[4:7]
	v_mfma_f32_16x16x32_bf16 v[0:3], v[186:189], v[222:225], v[0:3]
	s_setprio 0
	s_barrier
	s_add_i32 s60, s60, 2
	s_add_u32 s30, s30, 0x100
	s_addc_u32 s31, s31, 0
	s_add_u32 s58, s58, 0x100
	s_addc_u32 s59, s59, 0
	s_cmp_gt_u32 s60, 13
	s_cbranch_scc0 .LBB0_765
	s_and_b64 vcc, exec, s[10:11]
	s_cbranch_vccz .LBB0_768
	s_barrier

.LBB0_841:
	ds_read_b128 v[144:147], v153
	ds_read_b128 v[162:165], v153 offset:1024
	ds_read_b128 v[166:169], v153 offset:2048
	ds_read_b128 v[170:173], v153 offset:3072
	ds_read_b128 v[174:177], v154
	ds_read_b128 v[178:181], v154 offset:1024
	ds_read_b128 v[182:185], v154 offset:2048
	ds_read_b128 v[186:189], v154 offset:3072
	s_add_u32 s8, s36, 0xfff00080
	s_addc_u32 s9, s37, -1
	s_cmp_eq_u32 s65, 60
	s_cselect_b32 s39, s25, s9
	s_cselect_b32 s38, s31, s8
	s_cselect_b32 s9, s21, s64
	s_cselect_b32 s8, s60, s61
	v_lshl_add_u64 v[156:157], s[36:37], 0, v[136:137]
	s_add_i32 m0, s4, 0xc000
	ds_read_b128 v[190:193], v155
	ds_read_b128 v[198:201], v155 offset:1024
	ds_read_b128 v[202:205], v155 offset:2048
	ds_read_b128 v[206:209], v155 offset:3072
	ds_read_b128 v[210:213], v155 offset:4096
	ds_read_b128 v[214:217], v155 offset:5120
	ds_read_b128 v[218:221], v155 offset:6144
	ds_read_b128 v[222:225], v155 offset:7168
	global_load_lds_dwordx4 v[156:157], off
	v_lshl_add_u64 v[156:157], s[36:37], 0, v[138:139]
	s_add_i32 m0, s4, 0xe000
	s_nop 0
	global_load_lds_dwordx4 v[156:157], off
	s_waitcnt vmcnt(8)
	s_waitcnt lgkmcnt(0)
	s_barrier
	s_setprio 1
	s_waitcnt lgkmcnt(0)
	v_mfma_f32_16x16x32_bf16 v[124:127], v[144:147], v[190:193], v[124:127]
	v_mfma_f32_16x16x32_bf16 v[120:123], v[166:169], v[190:193], v[120:123]
	v_mfma_f32_16x16x32_bf16 v[108:111], v[144:147], v[202:205], v[108:111]
	v_mfma_f32_16x16x32_bf16 v[104:107], v[166:169], v[202:205], v[104:107]
	v_mfma_f32_16x16x32_bf16 v[92:95], v[144:147], v[210:213], v[92:95]
	v_mfma_f32_16x16x32_bf16 v[88:91], v[166:169], v[210:213], v[88:91]
	v_mfma_f32_16x16x32_bf16 v[76:79], v[144:147], v[218:221], v[76:79]
	v_mfma_f32_16x16x32_bf16 v[72:75], v[166:169], v[218:221], v[72:75]
	v_mfma_f32_16x16x32_bf16 v[124:127], v[162:165], v[198:201], v[124:127]
	v_mfma_f32_16x16x32_bf16 v[120:123], v[170:173], v[198:201], v[120:123]
	v_mfma_f32_16x16x32_bf16 v[108:111], v[162:165], v[206:209], v[108:111]
	v_mfma_f32_16x16x32_bf16 v[104:107], v[170:173], v[206:209], v[104:107]
	v_mfma_f32_16x16x32_bf16 v[92:95], v[162:165], v[214:217], v[92:95]
	v_mfma_f32_16x16x32_bf16 v[88:91], v[170:173], v[214:217], v[88:91]
	v_mfma_f32_16x16x32_bf16 v[76:79], v[162:165], v[222:225], v[76:79]
	v_mfma_f32_16x16x32_bf16 v[72:75], v[170:173], v[222:225], v[72:75]
	s_setprio 0
	s_setprio 1
	v_mfma_f32_16x16x32_bf16 v[116:119], v[174:177], v[190:193], v[116:119]
	v_mfma_f32_16x16x32_bf16 v[112:115], v[182:185], v[190:193], v[112:115]
	v_mfma_f32_16x16x32_bf16 v[100:103], v[174:177], v[202:205], v[100:103]
	v_mfma_f32_16x16x32_bf16 v[96:99], v[182:185], v[202:205], v[96:99]
	v_mfma_f32_16x16x32_bf16 v[84:87], v[174:177], v[210:213], v[84:87]
	v_mfma_f32_16x16x32_bf16 v[80:83], v[182:185], v[210:213], v[80:83]
	v_mfma_f32_16x16x32_bf16 v[68:71], v[174:177], v[218:221], v[68:71]
	v_mfma_f32_16x16x32_bf16 v[64:67], v[182:185], v[218:221], v[64:67]
	v_mfma_f32_16x16x32_bf16 v[116:119], v[178:181], v[198:201], v[116:119]
	v_mfma_f32_16x16x32_bf16 v[112:115], v[186:189], v[198:201], v[112:115]
	v_mfma_f32_16x16x32_bf16 v[100:103], v[178:181], v[206:209], v[100:103]
	v_mfma_f32_16x16x32_bf16 v[96:99], v[186:189], v[206:209], v[96:99]
	v_mfma_f32_16x16x32_bf16 v[84:87], v[178:181], v[214:217], v[84:87]
	v_mfma_f32_16x16x32_bf16 v[80:83], v[186:189], v[214:217], v[80:83]
	v_mfma_f32_16x16x32_bf16 v[68:71], v[178:181], v[222:225], v[68:71]
	v_mfma_f32_16x16x32_bf16 v[64:67], v[186:189], v[222:225], v[64:67]
	s_setprio 0
	s_barrier
	s_add_i32 s66, s55, s3
	v_lshl_add_u64 v[156:157], s[8:9], 0, v[130:131]
	s_mov_b32 m0, s66
	ds_read_b128 v[190:193], v155 offset:16384
	ds_read_b128 v[198:201], v155 offset:17408
	ds_read_b128 v[202:205], v155 offset:18432
	ds_read_b128 v[206:209], v155 offset:19456
	ds_read_b128 v[210:213], v155 offset:20480
	ds_read_b128 v[214:217], v155 offset:21504
	ds_read_b128 v[218:221], v155 offset:22528
	ds_read_b128 v[222:225], v155 offset:23552
	global_load_lds_dwordx4 v[156:157], off
	s_add_i32 m0, s66, 0x2000
	s_add_u32 s66, s8, 0x100000
	v_lshl_add_u64 v[226:227], s[8:9], 0, v[134:135]
	s_addc_u32 s67, s9, 0
	s_add_i32 s73, s58, s3
	global_load_lds_dwordx4 v[226:227], off
	v_lshl_add_u64 v[228:229], s[66:67], 0, v[130:131]
	s_mov_b32 m0, s73
	v_lshl_add_u64 v[230:231], s[38:39], 0, v[132:133]
	global_load_lds_dwordx4 v[228:229], off
	v_lshl_add_u64 v[228:229], s[66:67], 0, v[134:135]
	s_add_i32 m0, s73, 0x2000
	s_nop 0
	global_load_lds_dwordx4 v[228:229], off
	s_waitcnt vmcnt(6)
	s_waitcnt lgkmcnt(0)
	s_barrier
	s_setprio 1
	s_waitcnt lgkmcnt(0)
	v_mfma_f32_16x16x32_bf16 v[60:63], v[144:147], v[190:193], v[60:63]
	v_mfma_f32_16x16x32_bf16 v[56:59], v[166:169], v[190:193], v[56:59]
	v_mfma_f32_16x16x32_bf16 v[44:47], v[144:147], v[202:205], v[44:47]
	v_mfma_f32_16x16x32_bf16 v[40:43], v[166:169], v[202:205], v[40:43]
	v_mfma_f32_16x16x32_bf16 v[28:31], v[144:147], v[210:213], v[28:31]
	v_mfma_f32_16x16x32_bf16 v[24:27], v[166:169], v[210:213], v[24:27]
	v_mfma_f32_16x16x32_bf16 v[12:15], v[144:147], v[218:221], v[12:15]
	v_mfma_f32_16x16x32_bf16 v[8:11], v[166:169], v[218:221], v[8:11]
	v_mfma_f32_16x16x32_bf16 v[60:63], v[162:165], v[198:201], v[60:63]
	v_mfma_f32_16x16x32_bf16 v[56:59], v[170:173], v[198:201], v[56:59]
	v_mfma_f32_16x16x32_bf16 v[44:47], v[162:165], v[206:209], v[44:47]
	v_mfma_f32_16x16x32_bf16 v[40:43], v[170:173], v[206:209], v[40:43]
	v_mfma_f32_16x16x32_bf16 v[28:31], v[162:165], v[214:217], v[28:31]
	v_mfma_f32_16x16x32_bf16 v[24:27], v[170:173], v[214:217], v[24:27]
	v_mfma_f32_16x16x32_bf16 v[12:15], v[162:165], v[222:225], v[12:15]
	v_mfma_f32_16x16x32_bf16 v[8:11], v[170:173], v[222:225], v[8:11]
	s_setprio 0
	s_setprio 1
	v_mfma_f32_16x16x32_bf16 v[52:55], v[174:177], v[190:193], v[52:55]
	v_mfma_f32_16x16x32_bf16 v[48:51], v[182:185], v[190:193], v[48:51]
	v_mfma_f32_16x16x32_bf16 v[36:39], v[174:177], v[202:205], v[36:39]
	v_mfma_f32_16x16x32_bf16 v[32:35], v[182:185], v[202:205], v[32:35]
	v_mfma_f32_16x16x32_bf16 v[20:23], v[174:177], v[210:213], v[20:23]
	v_mfma_f32_16x16x32_bf16 v[16:19], v[182:185], v[210:213], v[16:19]
	v_mfma_f32_16x16x32_bf16 v[4:7], v[174:177], v[218:221], v[4:7]
	v_mfma_f32_16x16x32_bf16 v[0:3], v[182:185], v[218:221], v[0:3]
	v_mfma_f32_16x16x32_bf16 v[52:55], v[178:181], v[198:201], v[52:55]
	v_mfma_f32_16x16x32_bf16 v[48:51], v[186:189], v[198:201], v[48:51]
	v_mfma_f32_16x16x32_bf16 v[36:39], v[178:181], v[206:209], v[36:39]
	v_mfma_f32_16x16x32_bf16 v[32:35], v[186:189], v[206:209], v[32:35]
	v_mfma_f32_16x16x32_bf16 v[20:23], v[178:181], v[214:217], v[20:23]
	v_mfma_f32_16x16x32_bf16 v[16:19], v[186:189], v[214:217], v[16:19]
	v_mfma_f32_16x16x32_bf16 v[4:7], v[178:181], v[222:225], v[4:7]
	v_mfma_f32_16x16x32_bf16 v[0:3], v[186:189], v[222:225], v[0:3]
	s_setprio 0
	s_barrier
	v_lshl_add_u64 v[228:229], s[38:39], 0, v[128:129]
	s_mov_b32 m0, s4
	s_nop 0
	global_load_lds_dwordx4 v[228:229], off
	s_mov_b32 m0, s5
	s_nop 0
	global_load_lds_dwordx4 v[230:231], off
	s_add_i32 s66, 0, 0x18000
	v_add_u32_e32 v158, s66, v149
	s_add_i32 s67, 0, 0x1c000
	ds_read_b128 v[144:147], v158
	ds_read_b128 v[162:165], v158 offset:1024
	ds_read_b128 v[166:169], v158 offset:2048
	ds_read_b128 v[170:173], v158 offset:3072
	v_add_u32_e32 v158, s67, v149
	ds_read_b128 v[174:177], v158
	ds_read_b128 v[178:181], v158 offset:1024
	ds_read_b128 v[182:185], v158 offset:2048
	ds_read_b128 v[186:189], v158 offset:3072
	s_add_u32 s38, s38, 0x100000
	s_addc_u32 s39, s39, 0
	s_mov_b32 m0, s16
	v_lshl_add_u64 v[232:233], s[38:39], 0, v[128:129]
	ds_read_b128 v[190:193], v155 offset:32768
	ds_read_b128 v[198:201], v155 offset:33792
	ds_read_b128 v[202:205], v155 offset:34816
	ds_read_b128 v[206:209], v155 offset:35840
	ds_read_b128 v[210:213], v155 offset:36864
	ds_read_b128 v[214:217], v155 offset:37888
	ds_read_b128 v[218:221], v155 offset:38912
	ds_read_b128 v[222:225], v155 offset:39936
	global_load_lds_dwordx4 v[232:233], off
	v_lshl_add_u64 v[232:233], s[38:39], 0, v[132:133]
	s_mov_b32 m0, s17
	s_nop 0
	global_load_lds_dwordx4 v[232:233], off
	s_waitcnt vmcnt(8)
	s_waitcnt lgkmcnt(0)
	s_barrier
	s_setprio 1
	s_waitcnt lgkmcnt(0)
	v_mfma_f32_16x16x32_bf16 v[124:127], v[144:147], v[190:193], v[124:127]
	v_mfma_f32_16x16x32_bf16 v[120:123], v[166:169], v[190:193], v[120:123]
	v_mfma_f32_16x16x32_bf16 v[108:111], v[144:147], v[202:205], v[108:111]
	v_mfma_f32_16x16x32_bf16 v[104:107], v[166:169], v[202:205], v[104:107]
	v_mfma_f32_16x16x32_bf16 v[92:95], v[144:147], v[210:213], v[92:95]
	v_mfma_f32_16x16x32_bf16 v[88:91], v[166:169], v[210:213], v[88:91]
	v_mfma_f32_16x16x32_bf16 v[76:79], v[144:147], v[218:221], v[76:79]
	v_mfma_f32_16x16x32_bf16 v[72:75], v[166:169], v[218:221], v[72:75]
	v_mfma_f32_16x16x32_bf16 v[124:127], v[162:165], v[198:201], v[124:127]
	v_mfma_f32_16x16x32_bf16 v[120:123], v[170:173], v[198:201], v[120:123]
	v_mfma_f32_16x16x32_bf16 v[108:111], v[162:165], v[206:209], v[108:111]
	v_mfma_f32_16x16x32_bf16 v[104:107], v[170:173], v[206:209], v[104:107]
	v_mfma_f32_16x16x32_bf16 v[92:95], v[162:165], v[214:217], v[92:95]
	v_mfma_f32_16x16x32_bf16 v[88:91], v[170:173], v[214:217], v[88:91]
	v_mfma_f32_16x16x32_bf16 v[76:79], v[162:165], v[222:225], v[76:79]
	v_mfma_f32_16x16x32_bf16 v[72:75], v[170:173], v[222:225], v[72:75]
	s_setprio 0
	s_setprio 1
	v_mfma_f32_16x16x32_bf16 v[116:119], v[174:177], v[190:193], v[116:119]
	v_mfma_f32_16x16x32_bf16 v[112:115], v[182:185], v[190:193], v[112:115]
	v_mfma_f32_16x16x32_bf16 v[100:103], v[174:177], v[202:205], v[100:103]
	v_mfma_f32_16x16x32_bf16 v[96:99], v[182:185], v[202:205], v[96:99]
	v_mfma_f32_16x16x32_bf16 v[84:87], v[174:177], v[210:213], v[84:87]
	v_mfma_f32_16x16x32_bf16 v[80:83], v[182:185], v[210:213], v[80:83]
	v_mfma_f32_16x16x32_bf16 v[68:71], v[174:177], v[218:221], v[68:71]
	v_mfma_f32_16x16x32_bf16 v[64:67], v[182:185], v[218:221], v[64:67]
	v_mfma_f32_16x16x32_bf16 v[116:119], v[178:181], v[198:201], v[116:119]
	v_mfma_f32_16x16x32_bf16 v[112:115], v[186:189], v[198:201], v[112:115]
	v_mfma_f32_16x16x32_bf16 v[100:103], v[178:181], v[206:209], v[100:103]
	v_mfma_f32_16x16x32_bf16 v[96:99], v[186:189], v[206:209], v[96:99]
	v_mfma_f32_16x16x32_bf16 v[84:87], v[178:181], v[214:217], v[84:87]
	v_mfma_f32_16x16x32_bf16 v[80:83], v[186:189], v[214:217], v[80:83]
	v_mfma_f32_16x16x32_bf16 v[68:71], v[178:181], v[222:225], v[68:71]
	v_mfma_f32_16x16x32_bf16 v[64:67], v[186:189], v[222:225], v[64:67]
	s_setprio 0
	s_barrier
	s_add_i32 s38, s66, s3
	v_lshl_add_u64 v[156:157], v[156:157], 0, s[12:13]
	s_mov_b32 m0, s38
	ds_read_b128 v[190:193], v155 offset:49152
	ds_read_b128 v[198:201], v155 offset:50176
	ds_read_b128 v[202:205], v155 offset:51200
	ds_read_b128 v[206:209], v155 offset:52224
	ds_read_b128 v[210:213], v155 offset:53248
	ds_read_b128 v[214:217], v155 offset:54272
	ds_read_b128 v[218:221], v155 offset:55296
	ds_read_b128 v[222:225], v155 offset:56320
	global_load_lds_dwordx4 v[156:157], off
	s_add_i32 m0, s38, 0x2000
	s_add_u32 s8, s8, 0x100080
	v_lshl_add_u64 v[156:157], v[226:227], 0, s[12:13]
	s_addc_u32 s9, s9, 0
	s_add_i32 s38, s67, s3
	global_load_lds_dwordx4 v[156:157], off
	v_lshl_add_u64 v[156:157], s[8:9], 0, v[130:131]
	s_mov_b32 m0, s38
	s_nop 0
	global_load_lds_dwordx4 v[156:157], off
	v_lshl_add_u64 v[156:157], s[8:9], 0, v[134:135]
	s_add_i32 m0, s38, 0x2000
	s_nop 0
	global_load_lds_dwordx4 v[156:157], off
	v_lshl_add_u64 v[156:157], v[228:229], 0, s[12:13]
	s_mov_b32 m0, s40
	s_nop 0
	global_load_lds_dwordx4 v[156:157], off
	v_lshl_add_u64 v[156:157], v[230:231], 0, s[12:13]
	s_mov_b32 m0, s41
	s_nop 0
	global_load_lds_dwordx4 v[156:157], off
	s_waitcnt vmcnt(8)
	s_waitcnt lgkmcnt(0)
	s_barrier
	s_setprio 1
	s_waitcnt lgkmcnt(0)
	v_mfma_f32_16x16x32_bf16 v[60:63], v[144:147], v[190:193], v[60:63]
	v_mfma_f32_16x16x32_bf16 v[56:59], v[166:169], v[190:193], v[56:59]
	v_mfma_f32_16x16x32_bf16 v[44:47], v[144:147], v[202:205], v[44:47]
	v_mfma_f32_16x16x32_bf16 v[40:43], v[166:169], v[202:205], v[40:43]
	v_mfma_f32_16x16x32_bf16 v[28:31], v[144:147], v[210:213], v[28:31]
	v_mfma_f32_16x16x32_bf16 v[24:27], v[166:169], v[210:213], v[24:27]
	v_mfma_f32_16x16x32_bf16 v[12:15], v[144:147], v[218:221], v[12:15]
	v_mfma_f32_16x16x32_bf16 v[8:11], v[166:169], v[218:221], v[8:11]
	v_mfma_f32_16x16x32_bf16 v[60:63], v[162:165], v[198:201], v[60:63]
	v_mfma_f32_16x16x32_bf16 v[56:59], v[170:173], v[198:201], v[56:59]
	v_mfma_f32_16x16x32_bf16 v[44:47], v[162:165], v[206:209], v[44:47]
	v_mfma_f32_16x16x32_bf16 v[40:43], v[170:173], v[206:209], v[40:43]
	v_mfma_f32_16x16x32_bf16 v[28:31], v[162:165], v[214:217], v[28:31]
	v_mfma_f32_16x16x32_bf16 v[24:27], v[170:173], v[214:217], v[24:27]
	v_mfma_f32_16x16x32_bf16 v[12:15], v[162:165], v[222:225], v[12:15]
	v_mfma_f32_16x16x32_bf16 v[8:11], v[170:173], v[222:225], v[8:11]
	s_setprio 0
	s_setprio 1
	v_mfma_f32_16x16x32_bf16 v[52:55], v[174:177], v[190:193], v[52:55]
	v_mfma_f32_16x16x32_bf16 v[48:51], v[182:185], v[190:193], v[48:51]
	v_mfma_f32_16x16x32_bf16 v[36:39], v[174:177], v[202:205], v[36:39]
	v_mfma_f32_16x16x32_bf16 v[32:35], v[182:185], v[202:205], v[32:35]
	v_mfma_f32_16x16x32_bf16 v[20:23], v[174:177], v[210:213], v[20:23]
	v_mfma_f32_16x16x32_bf16 v[16:19], v[182:185], v[210:213], v[16:19]
	v_mfma_f32_16x16x32_bf16 v[4:7], v[174:177], v[218:221], v[4:7]
	v_mfma_f32_16x16x32_bf16 v[0:3], v[182:185], v[218:221], v[0:3]
	v_mfma_f32_16x16x32_bf16 v[52:55], v[178:181], v[198:201], v[52:55]
	v_mfma_f32_16x16x32_bf16 v[48:51], v[186:189], v[198:201], v[48:51]
	v_mfma_f32_16x16x32_bf16 v[36:39], v[178:181], v[206:209], v[36:39]
	v_mfma_f32_16x16x32_bf16 v[32:35], v[186:189], v[206:209], v[32:35]
	v_mfma_f32_16x16x32_bf16 v[20:23], v[178:181], v[214:217], v[20:23]
	v_mfma_f32_16x16x32_bf16 v[16:19], v[186:189], v[214:217], v[16:19]
	v_mfma_f32_16x16x32_bf16 v[4:7], v[178:181], v[222:225], v[4:7]
	v_mfma_f32_16x16x32_bf16 v[0:3], v[186:189], v[222:225], v[0:3]
	s_setprio 0
	s_barrier
	s_add_i32 s65, s65, 2
	s_add_u32 s36, s36, 0x100
	s_addc_u32 s37, s37, 0
	s_add_u32 s61, s61, 0x100
	s_addc_u32 s64, s64, 0
	s_cmp_gt_u32 s65, 61
	s_cbranch_scc0 .LBB0_841
	s_and_b64 vcc, exec, s[14:15]
	s_cbranch_vccz .LBB0_844
	s_barrier

.LBB0_938:
	ds_read_b128 v[146:149], v169
	ds_read_b128 v[150:153], v169 offset:1024
	ds_read_b128 v[154:157], v169 offset:2048
	ds_read_b128 v[174:177], v169 offset:3072
	ds_read_b128 v[178:181], v170
	ds_read_b128 v[182:185], v170 offset:1024
	ds_read_b128 v[186:189], v170 offset:2048
	ds_read_b128 v[190:193], v170 offset:3072
	s_add_u32 s8, s26, 0xfffc0080
	s_addc_u32 s9, s27, -1
	s_cmp_eq_u32 s61, 12
	s_cselect_b32 s29, s15, s9
	s_cselect_b32 s28, s55, s8
	s_cselect_b32 s9, s13, s60
	s_cselect_b32 s8, s58, s59
	v_lshl_add_u64 v[230:231], s[26:27], 0, v[138:139]
	s_add_i32 m0, s5, 0xc000
	ds_read_b128 v[198:201], v171
	ds_read_b128 v[202:205], v171 offset:1024
	ds_read_b128 v[206:209], v171 offset:2048
	ds_read_b128 v[210:213], v171 offset:3072
	ds_read_b128 v[214:217], v171 offset:4096
	ds_read_b128 v[218:221], v171 offset:5120
	ds_read_b128 v[222:225], v171 offset:6144
	ds_read_b128 v[226:229], v171 offset:7168
	global_load_lds_dwordx4 v[230:231], off
	v_lshl_add_u64 v[230:231], s[26:27], 0, v[140:141]
	s_add_i32 m0, s5, 0xe000
	s_nop 0
	global_load_lds_dwordx4 v[230:231], off
	s_waitcnt vmcnt(8)
	s_waitcnt lgkmcnt(0)
	s_barrier
	s_setprio 1
	s_waitcnt lgkmcnt(0)
	v_mfma_f32_16x16x32_bf16 v[124:127], v[146:149], v[198:201], v[124:127]
	v_mfma_f32_16x16x32_bf16 v[120:123], v[154:157], v[198:201], v[120:123]
	v_mfma_f32_16x16x32_bf16 v[116:119], v[146:149], v[206:209], v[116:119]
	v_mfma_f32_16x16x32_bf16 v[108:111], v[154:157], v[206:209], v[108:111]
	v_mfma_f32_16x16x32_bf16 v[100:103], v[146:149], v[214:217], v[100:103]
	v_mfma_f32_16x16x32_bf16 v[92:95], v[154:157], v[214:217], v[92:95]
	v_mfma_f32_16x16x32_bf16 v[84:87], v[146:149], v[222:225], v[84:87]
	v_mfma_f32_16x16x32_bf16 v[76:79], v[154:157], v[222:225], v[76:79]
	v_mfma_f32_16x16x32_bf16 v[124:127], v[150:153], v[202:205], v[124:127]
	v_mfma_f32_16x16x32_bf16 v[120:123], v[174:177], v[202:205], v[120:123]
	v_mfma_f32_16x16x32_bf16 v[116:119], v[150:153], v[210:213], v[116:119]
	v_mfma_f32_16x16x32_bf16 v[108:111], v[174:177], v[210:213], v[108:111]
	v_mfma_f32_16x16x32_bf16 v[100:103], v[150:153], v[218:221], v[100:103]
	v_mfma_f32_16x16x32_bf16 v[92:95], v[174:177], v[218:221], v[92:95]
	v_mfma_f32_16x16x32_bf16 v[84:87], v[150:153], v[226:229], v[84:87]
	v_mfma_f32_16x16x32_bf16 v[76:79], v[174:177], v[226:229], v[76:79]
	s_setprio 0
	s_setprio 1
	v_mfma_f32_16x16x32_bf16 v[112:115], v[178:181], v[198:201], v[112:115]
	v_mfma_f32_16x16x32_bf16 v[104:107], v[186:189], v[198:201], v[104:107]
	v_mfma_f32_16x16x32_bf16 v[96:99], v[178:181], v[206:209], v[96:99]
	v_mfma_f32_16x16x32_bf16 v[88:91], v[186:189], v[206:209], v[88:91]
	v_mfma_f32_16x16x32_bf16 v[80:83], v[178:181], v[214:217], v[80:83]
	v_mfma_f32_16x16x32_bf16 v[72:75], v[186:189], v[214:217], v[72:75]
	v_mfma_f32_16x16x32_bf16 v[68:71], v[178:181], v[222:225], v[68:71]
	v_mfma_f32_16x16x32_bf16 v[64:67], v[186:189], v[222:225], v[64:67]
	v_mfma_f32_16x16x32_bf16 v[112:115], v[182:185], v[202:205], v[112:115]
	v_mfma_f32_16x16x32_bf16 v[104:107], v[190:193], v[202:205], v[104:107]
	v_mfma_f32_16x16x32_bf16 v[96:99], v[182:185], v[210:213], v[96:99]
	v_mfma_f32_16x16x32_bf16 v[88:91], v[190:193], v[210:213], v[88:91]
	v_mfma_f32_16x16x32_bf16 v[80:83], v[182:185], v[218:221], v[80:83]
	v_mfma_f32_16x16x32_bf16 v[72:75], v[190:193], v[218:221], v[72:75]
	v_mfma_f32_16x16x32_bf16 v[68:71], v[182:185], v[226:229], v[68:71]
	v_mfma_f32_16x16x32_bf16 v[64:67], v[190:193], v[226:229], v[64:67]
	s_setprio 0
	s_barrier
	s_add_i32 s62, s37, s3
	v_lshl_add_u64 v[230:231], s[8:9], 0, v[132:133]
	s_mov_b32 m0, s62
	ds_read_b128 v[198:201], v171 offset:16384
	ds_read_b128 v[202:205], v171 offset:17408
	ds_read_b128 v[206:209], v171 offset:18432
	ds_read_b128 v[210:213], v171 offset:19456
	ds_read_b128 v[214:217], v171 offset:20480
	ds_read_b128 v[218:221], v171 offset:21504
	ds_read_b128 v[222:225], v171 offset:22528
	ds_read_b128 v[226:229], v171 offset:23552
	global_load_lds_dwordx4 v[230:231], off
	s_add_i32 m0, s62, 0x2000
	s_add_u32 s62, s8, 0x40000
	v_lshl_add_u64 v[232:233], s[8:9], 0, v[128:129]
	s_addc_u32 s63, s9, 0
	s_add_i32 s64, s38, s3
	global_load_lds_dwordx4 v[232:233], off
	v_lshl_add_u64 v[234:235], s[62:63], 0, v[132:133]
	s_mov_b32 m0, s64
	v_lshl_add_u64 v[236:237], s[28:29], 0, v[130:131]
	global_load_lds_dwordx4 v[234:235], off
	v_lshl_add_u64 v[234:235], s[62:63], 0, v[128:129]
	s_add_i32 m0, s64, 0x2000
	s_nop 0
	global_load_lds_dwordx4 v[234:235], off
	s_waitcnt vmcnt(6)
	s_waitcnt lgkmcnt(0)
	s_barrier
	s_setprio 1
	s_waitcnt lgkmcnt(0)
	v_mfma_f32_16x16x32_bf16 v[60:63], v[146:149], v[198:201], v[60:63]
	v_mfma_f32_16x16x32_bf16 v[56:59], v[154:157], v[198:201], v[56:59]
	v_mfma_f32_16x16x32_bf16 v[52:55], v[146:149], v[206:209], v[52:55]
	v_mfma_f32_16x16x32_bf16 v[44:47], v[154:157], v[206:209], v[44:47]
	v_mfma_f32_16x16x32_bf16 v[32:35], v[146:149], v[214:217], v[32:35]
	v_mfma_f32_16x16x32_bf16 v[24:27], v[154:157], v[214:217], v[24:27]
	v_mfma_f32_16x16x32_bf16 v[20:23], v[146:149], v[222:225], v[20:23]
	v_mfma_f32_16x16x32_bf16 v[12:15], v[154:157], v[222:225], v[12:15]
	v_mfma_f32_16x16x32_bf16 v[60:63], v[150:153], v[202:205], v[60:63]
	v_mfma_f32_16x16x32_bf16 v[56:59], v[174:177], v[202:205], v[56:59]
	v_mfma_f32_16x16x32_bf16 v[52:55], v[150:153], v[210:213], v[52:55]
	v_mfma_f32_16x16x32_bf16 v[44:47], v[174:177], v[210:213], v[44:47]
	v_mfma_f32_16x16x32_bf16 v[32:35], v[150:153], v[218:221], v[32:35]
	v_mfma_f32_16x16x32_bf16 v[24:27], v[174:177], v[218:221], v[24:27]
	v_mfma_f32_16x16x32_bf16 v[20:23], v[150:153], v[226:229], v[20:23]
	v_mfma_f32_16x16x32_bf16 v[12:15], v[174:177], v[226:229], v[12:15]
	s_setprio 0
	s_setprio 1
	v_mfma_f32_16x16x32_bf16 v[48:51], v[178:181], v[198:201], v[48:51]
	v_mfma_f32_16x16x32_bf16 v[40:43], v[186:189], v[198:201], v[40:43]
	v_mfma_f32_16x16x32_bf16 v[36:39], v[178:181], v[206:209], v[36:39]
	v_mfma_f32_16x16x32_bf16 v[28:31], v[186:189], v[206:209], v[28:31]
	v_mfma_f32_16x16x32_bf16 v[16:19], v[178:181], v[214:217], v[16:19]
	v_mfma_f32_16x16x32_bf16 v[8:11], v[186:189], v[214:217], v[8:11]
	v_mfma_f32_16x16x32_bf16 v[4:7], v[178:181], v[222:225], v[4:7]
	v_mfma_f32_16x16x32_bf16 v[0:3], v[186:189], v[222:225], v[0:3]
	v_mfma_f32_16x16x32_bf16 v[48:51], v[182:185], v[202:205], v[48:51]
	v_mfma_f32_16x16x32_bf16 v[40:43], v[190:193], v[202:205], v[40:43]
	v_mfma_f32_16x16x32_bf16 v[36:39], v[182:185], v[210:213], v[36:39]
	v_mfma_f32_16x16x32_bf16 v[28:31], v[190:193], v[210:213], v[28:31]
	v_mfma_f32_16x16x32_bf16 v[16:19], v[182:185], v[218:221], v[16:19]
	v_mfma_f32_16x16x32_bf16 v[8:11], v[190:193], v[218:221], v[8:11]
	v_mfma_f32_16x16x32_bf16 v[4:7], v[182:185], v[226:229], v[4:7]
	v_mfma_f32_16x16x32_bf16 v[0:3], v[190:193], v[226:229], v[0:3]
	s_setprio 0
	s_barrier
	v_lshl_add_u64 v[234:235], s[28:29], 0, v[134:135]
	s_mov_b32 m0, s5
	s_nop 0
	global_load_lds_dwordx4 v[234:235], off
	s_mov_b32 m0, s25
	s_nop 0
	global_load_lds_dwordx4 v[236:237], off
	s_add_i32 s62, 0, 0x18000
	s_add_i32 s63, 0, 0x1c000
	v_add_u32_e32 v174, s62, v162
	v_add_u32_e32 v190, s63, v162
	ds_read_b128 v[146:149], v174
	ds_read_b128 v[150:153], v174 offset:1024
	ds_read_b128 v[154:157], v174 offset:2048
	ds_read_b128 v[174:177], v174 offset:3072
	ds_read_b128 v[178:181], v190
	ds_read_b128 v[182:185], v190 offset:1024
	ds_read_b128 v[186:189], v190 offset:2048
	ds_read_b128 v[190:193], v190 offset:3072
	s_add_u32 s28, s28, 0x40000
	s_addc_u32 s29, s29, 0
	s_mov_b32 m0, s30
	v_lshl_add_u64 v[238:239], s[28:29], 0, v[134:135]
	ds_read_b128 v[198:201], v171 offset:32768
	ds_read_b128 v[202:205], v171 offset:33792
	ds_read_b128 v[206:209], v171 offset:34816
	ds_read_b128 v[210:213], v171 offset:35840
	ds_read_b128 v[214:217], v171 offset:36864
	ds_read_b128 v[218:221], v171 offset:37888
	ds_read_b128 v[222:225], v171 offset:38912
	ds_read_b128 v[226:229], v171 offset:39936
	global_load_lds_dwordx4 v[238:239], off
	v_lshl_add_u64 v[238:239], s[28:29], 0, v[130:131]
	s_mov_b32 m0, s31
	s_nop 0
	global_load_lds_dwordx4 v[238:239], off
	s_waitcnt vmcnt(8)
	s_waitcnt lgkmcnt(0)
	s_barrier
	s_setprio 1
	s_waitcnt lgkmcnt(0)
	v_mfma_f32_16x16x32_bf16 v[124:127], v[146:149], v[198:201], v[124:127]
	v_mfma_f32_16x16x32_bf16 v[120:123], v[154:157], v[198:201], v[120:123]
	v_mfma_f32_16x16x32_bf16 v[116:119], v[146:149], v[206:209], v[116:119]
	v_mfma_f32_16x16x32_bf16 v[108:111], v[154:157], v[206:209], v[108:111]
	v_mfma_f32_16x16x32_bf16 v[100:103], v[146:149], v[214:217], v[100:103]
	v_mfma_f32_16x16x32_bf16 v[92:95], v[154:157], v[214:217], v[92:95]
	v_mfma_f32_16x16x32_bf16 v[84:87], v[146:149], v[222:225], v[84:87]
	v_mfma_f32_16x16x32_bf16 v[76:79], v[154:157], v[222:225], v[76:79]
	v_mfma_f32_16x16x32_bf16 v[124:127], v[150:153], v[202:205], v[124:127]
	v_mfma_f32_16x16x32_bf16 v[120:123], v[174:177], v[202:205], v[120:123]
	v_mfma_f32_16x16x32_bf16 v[116:119], v[150:153], v[210:213], v[116:119]
	v_mfma_f32_16x16x32_bf16 v[108:111], v[174:177], v[210:213], v[108:111]
	v_mfma_f32_16x16x32_bf16 v[100:103], v[150:153], v[218:221], v[100:103]
	v_mfma_f32_16x16x32_bf16 v[92:95], v[174:177], v[218:221], v[92:95]
	v_mfma_f32_16x16x32_bf16 v[84:87], v[150:153], v[226:229], v[84:87]
	v_mfma_f32_16x16x32_bf16 v[76:79], v[174:177], v[226:229], v[76:79]
	s_setprio 0
	s_setprio 1
	v_mfma_f32_16x16x32_bf16 v[112:115], v[178:181], v[198:201], v[112:115]
	v_mfma_f32_16x16x32_bf16 v[104:107], v[186:189], v[198:201], v[104:107]
	v_mfma_f32_16x16x32_bf16 v[96:99], v[178:181], v[206:209], v[96:99]
	v_mfma_f32_16x16x32_bf16 v[88:91], v[186:189], v[206:209], v[88:91]
	v_mfma_f32_16x16x32_bf16 v[80:83], v[178:181], v[214:217], v[80:83]
	v_mfma_f32_16x16x32_bf16 v[72:75], v[186:189], v[214:217], v[72:75]
	v_mfma_f32_16x16x32_bf16 v[68:71], v[178:181], v[222:225], v[68:71]
	v_mfma_f32_16x16x32_bf16 v[64:67], v[186:189], v[222:225], v[64:67]
	v_mfma_f32_16x16x32_bf16 v[112:115], v[182:185], v[202:205], v[112:115]
	v_mfma_f32_16x16x32_bf16 v[104:107], v[190:193], v[202:205], v[104:107]
	v_mfma_f32_16x16x32_bf16 v[96:99], v[182:185], v[210:213], v[96:99]
	v_mfma_f32_16x16x32_bf16 v[88:91], v[190:193], v[210:213], v[88:91]
	v_mfma_f32_16x16x32_bf16 v[80:83], v[182:185], v[218:221], v[80:83]
	v_mfma_f32_16x16x32_bf16 v[72:75], v[190:193], v[218:221], v[72:75]
	v_mfma_f32_16x16x32_bf16 v[68:71], v[182:185], v[226:229], v[68:71]
	v_mfma_f32_16x16x32_bf16 v[64:67], v[190:193], v[226:229], v[64:67]
	s_setprio 0
	s_barrier
	s_add_i32 s28, s62, s3
	v_lshl_add_u64 v[230:231], v[230:231], 0, s[6:7]
	s_mov_b32 m0, s28
	ds_read_b128 v[198:201], v171 offset:49152
	ds_read_b128 v[202:205], v171 offset:50176
	ds_read_b128 v[206:209], v171 offset:51200
	ds_read_b128 v[210:213], v171 offset:52224
	ds_read_b128 v[214:217], v171 offset:53248
	ds_read_b128 v[218:221], v171 offset:54272
	ds_read_b128 v[222:225], v171 offset:55296
	ds_read_b128 v[226:229], v171 offset:56320
	global_load_lds_dwordx4 v[230:231], off
	s_add_i32 m0, s28, 0x2000
	s_add_u32 s8, s8, 0x40080
	v_lshl_add_u64 v[230:231], v[232:233], 0, s[6:7]
	s_addc_u32 s9, s9, 0
	s_add_i32 s28, s63, s3
	global_load_lds_dwordx4 v[230:231], off
	v_lshl_add_u64 v[230:231], s[8:9], 0, v[132:133]
	s_mov_b32 m0, s28
	s_nop 0
	global_load_lds_dwordx4 v[230:231], off
	v_lshl_add_u64 v[230:231], s[8:9], 0, v[128:129]
	s_add_i32 m0, s28, 0x2000
	s_nop 0
	global_load_lds_dwordx4 v[230:231], off
	v_lshl_add_u64 v[230:231], v[234:235], 0, s[6:7]
	s_mov_b32 m0, s33
	s_nop 0
	global_load_lds_dwordx4 v[230:231], off
	v_lshl_add_u64 v[230:231], v[236:237], 0, s[6:7]
	s_mov_b32 m0, s36
	s_nop 0
	global_load_lds_dwordx4 v[230:231], off
	s_waitcnt vmcnt(8)
	s_waitcnt lgkmcnt(0)
	s_barrier
	s_setprio 1
	s_waitcnt lgkmcnt(0)
	v_mfma_f32_16x16x32_bf16 v[60:63], v[146:149], v[198:201], v[60:63]
	v_mfma_f32_16x16x32_bf16 v[56:59], v[154:157], v[198:201], v[56:59]
	v_mfma_f32_16x16x32_bf16 v[52:55], v[146:149], v[206:209], v[52:55]
	v_mfma_f32_16x16x32_bf16 v[44:47], v[154:157], v[206:209], v[44:47]
	v_mfma_f32_16x16x32_bf16 v[32:35], v[146:149], v[214:217], v[32:35]
	v_mfma_f32_16x16x32_bf16 v[24:27], v[154:157], v[214:217], v[24:27]
	v_mfma_f32_16x16x32_bf16 v[20:23], v[146:149], v[222:225], v[20:23]
	v_mfma_f32_16x16x32_bf16 v[12:15], v[154:157], v[222:225], v[12:15]
	v_mfma_f32_16x16x32_bf16 v[60:63], v[150:153], v[202:205], v[60:63]
	v_mfma_f32_16x16x32_bf16 v[56:59], v[174:177], v[202:205], v[56:59]
	v_mfma_f32_16x16x32_bf16 v[52:55], v[150:153], v[210:213], v[52:55]
	v_mfma_f32_16x16x32_bf16 v[44:47], v[174:177], v[210:213], v[44:47]
	v_mfma_f32_16x16x32_bf16 v[32:35], v[150:153], v[218:221], v[32:35]
	v_mfma_f32_16x16x32_bf16 v[24:27], v[174:177], v[218:221], v[24:27]
	v_mfma_f32_16x16x32_bf16 v[20:23], v[150:153], v[226:229], v[20:23]
	v_mfma_f32_16x16x32_bf16 v[12:15], v[174:177], v[226:229], v[12:15]
	s_setprio 0
	s_setprio 1
	v_mfma_f32_16x16x32_bf16 v[48:51], v[178:181], v[198:201], v[48:51]
	v_mfma_f32_16x16x32_bf16 v[40:43], v[186:189], v[198:201], v[40:43]
	v_mfma_f32_16x16x32_bf16 v[36:39], v[178:181], v[206:209], v[36:39]
	v_mfma_f32_16x16x32_bf16 v[28:31], v[186:189], v[206:209], v[28:31]
	v_mfma_f32_16x16x32_bf16 v[16:19], v[178:181], v[214:217], v[16:19]
	v_mfma_f32_16x16x32_bf16 v[8:11], v[186:189], v[214:217], v[8:11]
	v_mfma_f32_16x16x32_bf16 v[4:7], v[178:181], v[222:225], v[4:7]
	v_mfma_f32_16x16x32_bf16 v[0:3], v[186:189], v[222:225], v[0:3]
	v_mfma_f32_16x16x32_bf16 v[48:51], v[182:185], v[202:205], v[48:51]
	v_mfma_f32_16x16x32_bf16 v[40:43], v[190:193], v[202:205], v[40:43]
	v_mfma_f32_16x16x32_bf16 v[36:39], v[182:185], v[210:213], v[36:39]
	v_mfma_f32_16x16x32_bf16 v[28:31], v[190:193], v[210:213], v[28:31]
	v_mfma_f32_16x16x32_bf16 v[16:19], v[182:185], v[218:221], v[16:19]
	v_mfma_f32_16x16x32_bf16 v[8:11], v[190:193], v[218:221], v[8:11]
	v_mfma_f32_16x16x32_bf16 v[4:7], v[182:185], v[226:229], v[4:7]
	v_mfma_f32_16x16x32_bf16 v[0:3], v[190:193], v[226:229], v[0:3]
	s_setprio 0
	s_barrier
	s_add_i32 s61, s61, 2
	s_add_u32 s26, s26, 0x100
	s_addc_u32 s27, s27, 0
	s_add_u32 s59, s59, 0x100
	s_addc_u32 s60, s60, 0
	s_cmp_gt_u32 s61, 13
	s_cbranch_scc0 .LBB0_938
	s_and_b64 vcc, exec, s[10:11]
	s_cbranch_vccz .LBB0_941
	s_barrier

.LBB0_1226:
	ds_read_b128 v[144:147], v151
	ds_read_b128 v[154:157], v151 offset:1024
	ds_read_b128 v[158:161], v151 offset:2048
	ds_read_b128 v[162:165], v151 offset:3072
	ds_read_b128 v[166:169], v152
	ds_read_b128 v[170:173], v152 offset:1024
	ds_read_b128 v[174:177], v152 offset:2048
	ds_read_b128 v[178:181], v152 offset:3072
	s_add_u32 s8, s28, 0xfffc0080
	s_addc_u32 s9, s29, -1
	s_cmp_eq_u32 s58, 12
	s_cselect_b32 s31, s21, s9
	s_cselect_b32 s30, s27, s8
	s_cselect_b32 s9, s17, s57
	s_cselect_b32 s8, s53, s55
	v_lshl_add_u64 v[196:197], s[28:29], 0, v[136:137]
	s_add_i32 m0, s4, 0xc000
	ds_read_b128 v[182:185], v153
	ds_read_b128 v[186:189], v153 offset:1024
	ds_read_b128 v[190:193], v153 offset:2048
	ds_read_b128 v[200:203], v153 offset:3072
	ds_read_b128 v[204:207], v153 offset:4096
	ds_read_b128 v[208:211], v153 offset:5120
	ds_read_b128 v[212:215], v153 offset:6144
	ds_read_b128 v[216:219], v153 offset:7168
	global_load_lds_dwordx4 v[196:197], off
	v_lshl_add_u64 v[196:197], s[28:29], 0, v[138:139]
	s_add_i32 m0, s4, 0xe000
	s_nop 0
	global_load_lds_dwordx4 v[196:197], off
	s_waitcnt vmcnt(8)
	s_waitcnt lgkmcnt(0)
	s_barrier
	s_setprio 1
	s_waitcnt lgkmcnt(0)
	v_mfma_f32_16x16x32_bf16 v[124:127], v[144:147], v[182:185], v[124:127]
	v_mfma_f32_16x16x32_bf16 v[120:123], v[158:161], v[182:185], v[120:123]
	v_mfma_f32_16x16x32_bf16 v[108:111], v[144:147], v[190:193], v[108:111]
	v_mfma_f32_16x16x32_bf16 v[104:107], v[158:161], v[190:193], v[104:107]
	v_mfma_f32_16x16x32_bf16 v[92:95], v[144:147], v[204:207], v[92:95]
	v_mfma_f32_16x16x32_bf16 v[88:91], v[158:161], v[204:207], v[88:91]
	v_mfma_f32_16x16x32_bf16 v[76:79], v[144:147], v[212:215], v[76:79]
	v_mfma_f32_16x16x32_bf16 v[72:75], v[158:161], v[212:215], v[72:75]
	v_mfma_f32_16x16x32_bf16 v[124:127], v[154:157], v[186:189], v[124:127]
	v_mfma_f32_16x16x32_bf16 v[120:123], v[162:165], v[186:189], v[120:123]
	v_mfma_f32_16x16x32_bf16 v[108:111], v[154:157], v[200:203], v[108:111]
	v_mfma_f32_16x16x32_bf16 v[104:107], v[162:165], v[200:203], v[104:107]
	v_mfma_f32_16x16x32_bf16 v[92:95], v[154:157], v[208:211], v[92:95]
	v_mfma_f32_16x16x32_bf16 v[88:91], v[162:165], v[208:211], v[88:91]
	v_mfma_f32_16x16x32_bf16 v[76:79], v[154:157], v[216:219], v[76:79]
	v_mfma_f32_16x16x32_bf16 v[72:75], v[162:165], v[216:219], v[72:75]
	s_setprio 0
	s_setprio 1
	v_mfma_f32_16x16x32_bf16 v[116:119], v[166:169], v[182:185], v[116:119]
	v_mfma_f32_16x16x32_bf16 v[112:115], v[174:177], v[182:185], v[112:115]
	v_mfma_f32_16x16x32_bf16 v[100:103], v[166:169], v[190:193], v[100:103]
	v_mfma_f32_16x16x32_bf16 v[96:99], v[174:177], v[190:193], v[96:99]
	v_mfma_f32_16x16x32_bf16 v[84:87], v[166:169], v[204:207], v[84:87]
	v_mfma_f32_16x16x32_bf16 v[80:83], v[174:177], v[204:207], v[80:83]
	v_mfma_f32_16x16x32_bf16 v[68:71], v[166:169], v[212:215], v[68:71]
	v_mfma_f32_16x16x32_bf16 v[64:67], v[174:177], v[212:215], v[64:67]
	v_mfma_f32_16x16x32_bf16 v[116:119], v[170:173], v[186:189], v[116:119]
	v_mfma_f32_16x16x32_bf16 v[112:115], v[178:181], v[186:189], v[112:115]
	v_mfma_f32_16x16x32_bf16 v[100:103], v[170:173], v[200:203], v[100:103]
	v_mfma_f32_16x16x32_bf16 v[96:99], v[178:181], v[200:203], v[96:99]
	v_mfma_f32_16x16x32_bf16 v[84:87], v[170:173], v[208:211], v[84:87]
	v_mfma_f32_16x16x32_bf16 v[80:83], v[178:181], v[208:211], v[80:83]
	v_mfma_f32_16x16x32_bf16 v[68:71], v[170:173], v[216:219], v[68:71]
	v_mfma_f32_16x16x32_bf16 v[64:67], v[178:181], v[216:219], v[64:67]
	s_setprio 0
	s_barrier
	s_add_i32 s59, s40, s3
	v_lshl_add_u64 v[196:197], s[8:9], 0, v[130:131]
	s_mov_b32 m0, s59
	ds_read_b128 v[182:185], v153 offset:16384
	ds_read_b128 v[186:189], v153 offset:17408
	ds_read_b128 v[190:193], v153 offset:18432
	ds_read_b128 v[200:203], v153 offset:19456
	ds_read_b128 v[204:207], v153 offset:20480
	ds_read_b128 v[208:211], v153 offset:21504
	ds_read_b128 v[212:215], v153 offset:22528
	ds_read_b128 v[216:219], v153 offset:23552
	global_load_lds_dwordx4 v[196:197], off
	s_add_i32 m0, s59, 0x2000
	s_add_u32 s60, s8, 0x40000
	v_lshl_add_u64 v[220:221], s[8:9], 0, v[134:135]
	s_addc_u32 s61, s9, 0
	s_add_i32 s59, s41, s3
	global_load_lds_dwordx4 v[220:221], off
	v_lshl_add_u64 v[222:223], s[60:61], 0, v[130:131]
	s_mov_b32 m0, s59
	v_lshl_add_u64 v[224:225], s[30:31], 0, v[132:133]
	global_load_lds_dwordx4 v[222:223], off
	v_lshl_add_u64 v[222:223], s[60:61], 0, v[134:135]
	s_add_i32 m0, s59, 0x2000
	s_nop 0
	global_load_lds_dwordx4 v[222:223], off
	s_waitcnt vmcnt(6)
	s_waitcnt lgkmcnt(0)
	s_barrier
	s_setprio 1
	s_waitcnt lgkmcnt(0)
	v_mfma_f32_16x16x32_bf16 v[60:63], v[144:147], v[182:185], v[60:63]
	v_mfma_f32_16x16x32_bf16 v[56:59], v[158:161], v[182:185], v[56:59]
	v_mfma_f32_16x16x32_bf16 v[44:47], v[144:147], v[190:193], v[44:47]
	v_mfma_f32_16x16x32_bf16 v[40:43], v[158:161], v[190:193], v[40:43]
	v_mfma_f32_16x16x32_bf16 v[28:31], v[144:147], v[204:207], v[28:31]
	v_mfma_f32_16x16x32_bf16 v[24:27], v[158:161], v[204:207], v[24:27]
	v_mfma_f32_16x16x32_bf16 v[12:15], v[144:147], v[212:215], v[12:15]
	v_mfma_f32_16x16x32_bf16 v[8:11], v[158:161], v[212:215], v[8:11]
	v_mfma_f32_16x16x32_bf16 v[60:63], v[154:157], v[186:189], v[60:63]
	v_mfma_f32_16x16x32_bf16 v[56:59], v[162:165], v[186:189], v[56:59]
	v_mfma_f32_16x16x32_bf16 v[44:47], v[154:157], v[200:203], v[44:47]
	v_mfma_f32_16x16x32_bf16 v[40:43], v[162:165], v[200:203], v[40:43]
	v_mfma_f32_16x16x32_bf16 v[28:31], v[154:157], v[208:211], v[28:31]
	v_mfma_f32_16x16x32_bf16 v[24:27], v[162:165], v[208:211], v[24:27]
	v_mfma_f32_16x16x32_bf16 v[12:15], v[154:157], v[216:219], v[12:15]
	v_mfma_f32_16x16x32_bf16 v[8:11], v[162:165], v[216:219], v[8:11]
	s_setprio 0
	s_setprio 1
	v_mfma_f32_16x16x32_bf16 v[52:55], v[166:169], v[182:185], v[52:55]
	v_mfma_f32_16x16x32_bf16 v[48:51], v[174:177], v[182:185], v[48:51]
	v_mfma_f32_16x16x32_bf16 v[36:39], v[166:169], v[190:193], v[36:39]
	v_mfma_f32_16x16x32_bf16 v[32:35], v[174:177], v[190:193], v[32:35]
	v_mfma_f32_16x16x32_bf16 v[20:23], v[166:169], v[204:207], v[20:23]
	v_mfma_f32_16x16x32_bf16 v[16:19], v[174:177], v[204:207], v[16:19]
	v_mfma_f32_16x16x32_bf16 v[4:7], v[166:169], v[212:215], v[4:7]
	v_mfma_f32_16x16x32_bf16 v[0:3], v[174:177], v[212:215], v[0:3]
	v_mfma_f32_16x16x32_bf16 v[52:55], v[170:173], v[186:189], v[52:55]
	v_mfma_f32_16x16x32_bf16 v[48:51], v[178:181], v[186:189], v[48:51]
	v_mfma_f32_16x16x32_bf16 v[36:39], v[170:173], v[200:203], v[36:39]
	v_mfma_f32_16x16x32_bf16 v[32:35], v[178:181], v[200:203], v[32:35]
	v_mfma_f32_16x16x32_bf16 v[20:23], v[170:173], v[208:211], v[20:23]
	v_mfma_f32_16x16x32_bf16 v[16:19], v[178:181], v[208:211], v[16:19]
	v_mfma_f32_16x16x32_bf16 v[4:7], v[170:173], v[216:219], v[4:7]
	v_mfma_f32_16x16x32_bf16 v[0:3], v[178:181], v[216:219], v[0:3]
	s_setprio 0
	s_barrier
	v_lshl_add_u64 v[222:223], s[30:31], 0, v[128:129]
	s_mov_b32 m0, s4
	s_nop 0
	global_load_lds_dwordx4 v[222:223], off
	s_mov_b32 m0, s5
	s_nop 0
	global_load_lds_dwordx4 v[224:225], off
	s_add_i32 s59, 0, 0x18000
	s_add_i32 s60, 0, 0x1c000
	v_add_u32_e32 v162, s59, v149
	v_add_u32_e32 v178, s60, v149
	ds_read_b128 v[144:147], v162
	ds_read_b128 v[154:157], v162 offset:1024
	ds_read_b128 v[158:161], v162 offset:2048
	ds_read_b128 v[162:165], v162 offset:3072
	ds_read_b128 v[166:169], v178
	ds_read_b128 v[170:173], v178 offset:1024
	ds_read_b128 v[174:177], v178 offset:2048
	ds_read_b128 v[178:181], v178 offset:3072
	s_add_u32 s30, s30, 0x40000
	s_addc_u32 s31, s31, 0
	s_mov_b32 m0, s33
	v_lshl_add_u64 v[226:227], s[30:31], 0, v[128:129]
	ds_read_b128 v[182:185], v153 offset:32768
	ds_read_b128 v[186:189], v153 offset:33792
	ds_read_b128 v[190:193], v153 offset:34816
	ds_read_b128 v[200:203], v153 offset:35840
	ds_read_b128 v[204:207], v153 offset:36864
	ds_read_b128 v[208:211], v153 offset:37888
	ds_read_b128 v[212:215], v153 offset:38912
	ds_read_b128 v[216:219], v153 offset:39936
	global_load_lds_dwordx4 v[226:227], off
	v_lshl_add_u64 v[226:227], s[30:31], 0, v[132:133]
	s_mov_b32 m0, s36
	s_nop 0
	global_load_lds_dwordx4 v[226:227], off
	s_waitcnt vmcnt(8)
	s_waitcnt lgkmcnt(0)
	s_barrier
	s_setprio 1
	s_waitcnt lgkmcnt(0)
	v_mfma_f32_16x16x32_bf16 v[124:127], v[144:147], v[182:185], v[124:127]
	v_mfma_f32_16x16x32_bf16 v[120:123], v[158:161], v[182:185], v[120:123]
	v_mfma_f32_16x16x32_bf16 v[108:111], v[144:147], v[190:193], v[108:111]
	v_mfma_f32_16x16x32_bf16 v[104:107], v[158:161], v[190:193], v[104:107]
	v_mfma_f32_16x16x32_bf16 v[92:95], v[144:147], v[204:207], v[92:95]
	v_mfma_f32_16x16x32_bf16 v[88:91], v[158:161], v[204:207], v[88:91]
	v_mfma_f32_16x16x32_bf16 v[76:79], v[144:147], v[212:215], v[76:79]
	v_mfma_f32_16x16x32_bf16 v[72:75], v[158:161], v[212:215], v[72:75]
	v_mfma_f32_16x16x32_bf16 v[124:127], v[154:157], v[186:189], v[124:127]
	v_mfma_f32_16x16x32_bf16 v[120:123], v[162:165], v[186:189], v[120:123]
	v_mfma_f32_16x16x32_bf16 v[108:111], v[154:157], v[200:203], v[108:111]
	v_mfma_f32_16x16x32_bf16 v[104:107], v[162:165], v[200:203], v[104:107]
	v_mfma_f32_16x16x32_bf16 v[92:95], v[154:157], v[208:211], v[92:95]
	v_mfma_f32_16x16x32_bf16 v[88:91], v[162:165], v[208:211], v[88:91]
	v_mfma_f32_16x16x32_bf16 v[76:79], v[154:157], v[216:219], v[76:79]
	v_mfma_f32_16x16x32_bf16 v[72:75], v[162:165], v[216:219], v[72:75]
	s_setprio 0
	s_setprio 1
	v_mfma_f32_16x16x32_bf16 v[116:119], v[166:169], v[182:185], v[116:119]
	v_mfma_f32_16x16x32_bf16 v[112:115], v[174:177], v[182:185], v[112:115]
	v_mfma_f32_16x16x32_bf16 v[100:103], v[166:169], v[190:193], v[100:103]
	v_mfma_f32_16x16x32_bf16 v[96:99], v[174:177], v[190:193], v[96:99]
	v_mfma_f32_16x16x32_bf16 v[84:87], v[166:169], v[204:207], v[84:87]
	v_mfma_f32_16x16x32_bf16 v[80:83], v[174:177], v[204:207], v[80:83]
	v_mfma_f32_16x16x32_bf16 v[68:71], v[166:169], v[212:215], v[68:71]
	v_mfma_f32_16x16x32_bf16 v[64:67], v[174:177], v[212:215], v[64:67]
	v_mfma_f32_16x16x32_bf16 v[116:119], v[170:173], v[186:189], v[116:119]
	v_mfma_f32_16x16x32_bf16 v[112:115], v[178:181], v[186:189], v[112:115]
	v_mfma_f32_16x16x32_bf16 v[100:103], v[170:173], v[200:203], v[100:103]
	v_mfma_f32_16x16x32_bf16 v[96:99], v[178:181], v[200:203], v[96:99]
	v_mfma_f32_16x16x32_bf16 v[84:87], v[170:173], v[208:211], v[84:87]
	v_mfma_f32_16x16x32_bf16 v[80:83], v[178:181], v[208:211], v[80:83]
	v_mfma_f32_16x16x32_bf16 v[68:71], v[170:173], v[216:219], v[68:71]
	v_mfma_f32_16x16x32_bf16 v[64:67], v[178:181], v[216:219], v[64:67]
	s_setprio 0
	s_barrier
	s_add_i32 s30, s59, s3
	v_lshl_add_u64 v[196:197], v[196:197], 0, s[12:13]
	s_mov_b32 m0, s30
	ds_read_b128 v[182:185], v153 offset:49152
	ds_read_b128 v[186:189], v153 offset:50176
	ds_read_b128 v[190:193], v153 offset:51200
	ds_read_b128 v[200:203], v153 offset:52224
	ds_read_b128 v[204:207], v153 offset:53248
	ds_read_b128 v[208:211], v153 offset:54272
	ds_read_b128 v[212:215], v153 offset:55296
	ds_read_b128 v[216:219], v153 offset:56320
	global_load_lds_dwordx4 v[196:197], off
	s_add_i32 m0, s30, 0x2000
	s_add_u32 s8, s8, 0x40080
	v_lshl_add_u64 v[196:197], v[220:221], 0, s[12:13]
	s_addc_u32 s9, s9, 0
	s_add_i32 s30, s60, s3
	global_load_lds_dwordx4 v[196:197], off
	v_lshl_add_u64 v[196:197], s[8:9], 0, v[130:131]
	s_mov_b32 m0, s30
	s_nop 0
	global_load_lds_dwordx4 v[196:197], off
	v_lshl_add_u64 v[196:197], s[8:9], 0, v[134:135]
	s_add_i32 m0, s30, 0x2000
	s_nop 0
	global_load_lds_dwordx4 v[196:197], off
	v_lshl_add_u64 v[196:197], v[222:223], 0, s[12:13]
	s_mov_b32 m0, s38
	s_nop 0
	global_load_lds_dwordx4 v[196:197], off
	v_lshl_add_u64 v[196:197], v[224:225], 0, s[12:13]
	s_mov_b32 m0, s39
	s_nop 0
	global_load_lds_dwordx4 v[196:197], off
	s_waitcnt vmcnt(8)
	s_waitcnt lgkmcnt(0)
	s_barrier
	s_setprio 1
	s_waitcnt lgkmcnt(0)
	v_mfma_f32_16x16x32_bf16 v[60:63], v[144:147], v[182:185], v[60:63]
	v_mfma_f32_16x16x32_bf16 v[56:59], v[158:161], v[182:185], v[56:59]
	v_mfma_f32_16x16x32_bf16 v[44:47], v[144:147], v[190:193], v[44:47]
	v_mfma_f32_16x16x32_bf16 v[40:43], v[158:161], v[190:193], v[40:43]
	v_mfma_f32_16x16x32_bf16 v[28:31], v[144:147], v[204:207], v[28:31]
	v_mfma_f32_16x16x32_bf16 v[24:27], v[158:161], v[204:207], v[24:27]
	v_mfma_f32_16x16x32_bf16 v[12:15], v[144:147], v[212:215], v[12:15]
	v_mfma_f32_16x16x32_bf16 v[8:11], v[158:161], v[212:215], v[8:11]
	v_mfma_f32_16x16x32_bf16 v[60:63], v[154:157], v[186:189], v[60:63]
	v_mfma_f32_16x16x32_bf16 v[56:59], v[162:165], v[186:189], v[56:59]
	v_mfma_f32_16x16x32_bf16 v[44:47], v[154:157], v[200:203], v[44:47]
	v_mfma_f32_16x16x32_bf16 v[40:43], v[162:165], v[200:203], v[40:43]
	v_mfma_f32_16x16x32_bf16 v[28:31], v[154:157], v[208:211], v[28:31]
	v_mfma_f32_16x16x32_bf16 v[24:27], v[162:165], v[208:211], v[24:27]
	v_mfma_f32_16x16x32_bf16 v[12:15], v[154:157], v[216:219], v[12:15]
	v_mfma_f32_16x16x32_bf16 v[8:11], v[162:165], v[216:219], v[8:11]
	s_setprio 0
	s_setprio 1
	v_mfma_f32_16x16x32_bf16 v[52:55], v[166:169], v[182:185], v[52:55]
	v_mfma_f32_16x16x32_bf16 v[48:51], v[174:177], v[182:185], v[48:51]
	v_mfma_f32_16x16x32_bf16 v[36:39], v[166:169], v[190:193], v[36:39]
	v_mfma_f32_16x16x32_bf16 v[32:35], v[174:177], v[190:193], v[32:35]
	v_mfma_f32_16x16x32_bf16 v[20:23], v[166:169], v[204:207], v[20:23]
	v_mfma_f32_16x16x32_bf16 v[16:19], v[174:177], v[204:207], v[16:19]
	v_mfma_f32_16x16x32_bf16 v[4:7], v[166:169], v[212:215], v[4:7]
	v_mfma_f32_16x16x32_bf16 v[0:3], v[174:177], v[212:215], v[0:3]
	v_mfma_f32_16x16x32_bf16 v[52:55], v[170:173], v[186:189], v[52:55]
	v_mfma_f32_16x16x32_bf16 v[48:51], v[178:181], v[186:189], v[48:51]
	v_mfma_f32_16x16x32_bf16 v[36:39], v[170:173], v[200:203], v[36:39]
	v_mfma_f32_16x16x32_bf16 v[32:35], v[178:181], v[200:203], v[32:35]
	v_mfma_f32_16x16x32_bf16 v[20:23], v[170:173], v[208:211], v[20:23]
	v_mfma_f32_16x16x32_bf16 v[16:19], v[178:181], v[208:211], v[16:19]
	v_mfma_f32_16x16x32_bf16 v[4:7], v[170:173], v[216:219], v[4:7]
	v_mfma_f32_16x16x32_bf16 v[0:3], v[178:181], v[216:219], v[0:3]
	s_setprio 0
	s_barrier
	s_add_i32 s58, s58, 2
	s_add_u32 s28, s28, 0x100
	s_addc_u32 s29, s29, 0
	s_add_u32 s55, s55, 0x100
	s_addc_u32 s57, s57, 0
	s_cmp_gt_u32 s58, 13
	s_cbranch_scc0 .LBB0_1226
	s_and_b64 vcc, exec, s[14:15]
	s_cbranch_vccz .LBB0_1229
	s_barrier

.LBB0_1325:
	ds_read_b128 v[144:147], v154
	ds_read_b128 v[158:161], v154 offset:1024
	ds_read_b128 v[162:165], v154 offset:2048
	ds_read_b128 v[166:169], v154 offset:3072
	ds_read_b128 v[170:173], v155
	ds_read_b128 v[174:177], v155 offset:1024
	ds_read_b128 v[178:181], v155 offset:2048
	ds_read_b128 v[182:185], v155 offset:3072
	s_add_u32 s8, s24, 0xfffc0080
	s_addc_u32 s9, s25, -1
	s_cmp_eq_u32 s45, 12
	s_cselect_b32 s27, s15, s9
	s_cselect_b32 s26, s39, s8
	s_cselect_b32 s9, s13, s44
	s_cselect_b32 s8, s40, s41
	v_lshl_add_u64 v[148:149], s[24:25], 0, v[136:137]
	s_add_i32 m0, s4, 0xc000
	ds_read_b128 v[186:189], v156
	ds_read_b128 v[190:193], v156 offset:1024
	ds_read_b128 v[196:199], v156 offset:2048
	ds_read_b128 v[200:203], v156 offset:3072
	ds_read_b128 v[204:207], v156 offset:4096
	ds_read_b128 v[208:211], v156 offset:5120
	ds_read_b128 v[212:215], v156 offset:6144
	ds_read_b128 v[216:219], v156 offset:7168
	global_load_lds_dwordx4 v[148:149], off
	v_lshl_add_u64 v[148:149], s[24:25], 0, v[138:139]
	s_add_i32 m0, s4, 0xe000
	s_nop 0
	global_load_lds_dwordx4 v[148:149], off
	s_waitcnt vmcnt(8)
	s_waitcnt lgkmcnt(0)
	s_barrier
	s_setprio 1
	s_waitcnt lgkmcnt(0)
	v_mfma_f32_16x16x32_bf16 v[124:127], v[144:147], v[186:189], v[124:127]
	v_mfma_f32_16x16x32_bf16 v[120:123], v[162:165], v[186:189], v[120:123]
	v_mfma_f32_16x16x32_bf16 v[108:111], v[144:147], v[196:199], v[108:111]
	v_mfma_f32_16x16x32_bf16 v[104:107], v[162:165], v[196:199], v[104:107]
	v_mfma_f32_16x16x32_bf16 v[92:95], v[144:147], v[204:207], v[92:95]
	v_mfma_f32_16x16x32_bf16 v[88:91], v[162:165], v[204:207], v[88:91]
	v_mfma_f32_16x16x32_bf16 v[76:79], v[144:147], v[212:215], v[76:79]
	v_mfma_f32_16x16x32_bf16 v[72:75], v[162:165], v[212:215], v[72:75]
	v_mfma_f32_16x16x32_bf16 v[124:127], v[158:161], v[190:193], v[124:127]
	v_mfma_f32_16x16x32_bf16 v[120:123], v[166:169], v[190:193], v[120:123]
	v_mfma_f32_16x16x32_bf16 v[108:111], v[158:161], v[200:203], v[108:111]
	v_mfma_f32_16x16x32_bf16 v[104:107], v[166:169], v[200:203], v[104:107]
	v_mfma_f32_16x16x32_bf16 v[92:95], v[158:161], v[208:211], v[92:95]
	v_mfma_f32_16x16x32_bf16 v[88:91], v[166:169], v[208:211], v[88:91]
	v_mfma_f32_16x16x32_bf16 v[76:79], v[158:161], v[216:219], v[76:79]
	v_mfma_f32_16x16x32_bf16 v[72:75], v[166:169], v[216:219], v[72:75]
	s_setprio 0
	s_setprio 1
	v_mfma_f32_16x16x32_bf16 v[116:119], v[170:173], v[186:189], v[116:119]
	v_mfma_f32_16x16x32_bf16 v[112:115], v[178:181], v[186:189], v[112:115]
	v_mfma_f32_16x16x32_bf16 v[100:103], v[170:173], v[196:199], v[100:103]
	v_mfma_f32_16x16x32_bf16 v[96:99], v[178:181], v[196:199], v[96:99]
	v_mfma_f32_16x16x32_bf16 v[84:87], v[170:173], v[204:207], v[84:87]
	v_mfma_f32_16x16x32_bf16 v[80:83], v[178:181], v[204:207], v[80:83]
	v_mfma_f32_16x16x32_bf16 v[68:71], v[170:173], v[212:215], v[68:71]
	v_mfma_f32_16x16x32_bf16 v[64:67], v[178:181], v[212:215], v[64:67]
	v_mfma_f32_16x16x32_bf16 v[116:119], v[174:177], v[190:193], v[116:119]
	v_mfma_f32_16x16x32_bf16 v[112:115], v[182:185], v[190:193], v[112:115]
	v_mfma_f32_16x16x32_bf16 v[100:103], v[174:177], v[200:203], v[100:103]
	v_mfma_f32_16x16x32_bf16 v[96:99], v[182:185], v[200:203], v[96:99]
	v_mfma_f32_16x16x32_bf16 v[84:87], v[174:177], v[208:211], v[84:87]
	v_mfma_f32_16x16x32_bf16 v[80:83], v[182:185], v[208:211], v[80:83]
	v_mfma_f32_16x16x32_bf16 v[68:71], v[174:177], v[216:219], v[68:71]
	v_mfma_f32_16x16x32_bf16 v[64:67], v[182:185], v[216:219], v[64:67]
	s_setprio 0
	s_barrier
	s_add_i32 s46, s31, s3
	v_lshl_add_u64 v[148:149], s[8:9], 0, v[132:133]
	s_mov_b32 m0, s46
	ds_read_b128 v[186:189], v156 offset:16384
	ds_read_b128 v[190:193], v156 offset:17408
	ds_read_b128 v[196:199], v156 offset:18432
	ds_read_b128 v[200:203], v156 offset:19456
	ds_read_b128 v[204:207], v156 offset:20480
	ds_read_b128 v[208:211], v156 offset:21504
	ds_read_b128 v[212:215], v156 offset:22528
	ds_read_b128 v[216:219], v156 offset:23552
	global_load_lds_dwordx4 v[148:149], off
	s_add_i32 m0, s46, 0x2000
	s_add_u32 s46, s8, 0x40000
	v_lshl_add_u64 v[220:221], s[8:9], 0, v[128:129]
	s_addc_u32 s47, s9, 0
	s_add_i32 s50, s33, s3
	global_load_lds_dwordx4 v[220:221], off
	v_lshl_add_u64 v[222:223], s[46:47], 0, v[132:133]
	s_mov_b32 m0, s50
	v_lshl_add_u64 v[224:225], s[26:27], 0, v[130:131]
	global_load_lds_dwordx4 v[222:223], off
	v_lshl_add_u64 v[222:223], s[46:47], 0, v[128:129]
	s_add_i32 m0, s50, 0x2000
	s_nop 0
	global_load_lds_dwordx4 v[222:223], off
	s_waitcnt vmcnt(6)
	s_waitcnt lgkmcnt(0)
	s_barrier
	s_setprio 1
	s_waitcnt lgkmcnt(0)
	v_mfma_f32_16x16x32_bf16 v[60:63], v[144:147], v[186:189], v[60:63]
	v_mfma_f32_16x16x32_bf16 v[56:59], v[162:165], v[186:189], v[56:59]
	v_mfma_f32_16x16x32_bf16 v[44:47], v[144:147], v[196:199], v[44:47]
	v_mfma_f32_16x16x32_bf16 v[40:43], v[162:165], v[196:199], v[40:43]
	v_mfma_f32_16x16x32_bf16 v[28:31], v[144:147], v[204:207], v[28:31]
	v_mfma_f32_16x16x32_bf16 v[24:27], v[162:165], v[204:207], v[24:27]
	v_mfma_f32_16x16x32_bf16 v[12:15], v[144:147], v[212:215], v[12:15]
	v_mfma_f32_16x16x32_bf16 v[8:11], v[162:165], v[212:215], v[8:11]
	v_mfma_f32_16x16x32_bf16 v[60:63], v[158:161], v[190:193], v[60:63]
	v_mfma_f32_16x16x32_bf16 v[56:59], v[166:169], v[190:193], v[56:59]
	v_mfma_f32_16x16x32_bf16 v[44:47], v[158:161], v[200:203], v[44:47]
	v_mfma_f32_16x16x32_bf16 v[40:43], v[166:169], v[200:203], v[40:43]
	v_mfma_f32_16x16x32_bf16 v[28:31], v[158:161], v[208:211], v[28:31]
	v_mfma_f32_16x16x32_bf16 v[24:27], v[166:169], v[208:211], v[24:27]
	v_mfma_f32_16x16x32_bf16 v[12:15], v[158:161], v[216:219], v[12:15]
	v_mfma_f32_16x16x32_bf16 v[8:11], v[166:169], v[216:219], v[8:11]
	s_setprio 0
	s_setprio 1
	v_mfma_f32_16x16x32_bf16 v[52:55], v[170:173], v[186:189], v[52:55]
	v_mfma_f32_16x16x32_bf16 v[48:51], v[178:181], v[186:189], v[48:51]
	v_mfma_f32_16x16x32_bf16 v[36:39], v[170:173], v[196:199], v[36:39]
	v_mfma_f32_16x16x32_bf16 v[32:35], v[178:181], v[196:199], v[32:35]
	v_mfma_f32_16x16x32_bf16 v[20:23], v[170:173], v[204:207], v[20:23]
	v_mfma_f32_16x16x32_bf16 v[16:19], v[178:181], v[204:207], v[16:19]
	v_mfma_f32_16x16x32_bf16 v[4:7], v[170:173], v[212:215], v[4:7]
	v_mfma_f32_16x16x32_bf16 v[0:3], v[178:181], v[212:215], v[0:3]
	v_mfma_f32_16x16x32_bf16 v[52:55], v[174:177], v[190:193], v[52:55]
	v_mfma_f32_16x16x32_bf16 v[48:51], v[182:185], v[190:193], v[48:51]
	v_mfma_f32_16x16x32_bf16 v[36:39], v[174:177], v[200:203], v[36:39]
	v_mfma_f32_16x16x32_bf16 v[32:35], v[182:185], v[200:203], v[32:35]
	v_mfma_f32_16x16x32_bf16 v[20:23], v[174:177], v[208:211], v[20:23]
	v_mfma_f32_16x16x32_bf16 v[16:19], v[182:185], v[208:211], v[16:19]
	v_mfma_f32_16x16x32_bf16 v[4:7], v[174:177], v[216:219], v[4:7]
	v_mfma_f32_16x16x32_bf16 v[0:3], v[182:185], v[216:219], v[0:3]
	s_setprio 0
	s_barrier
	v_lshl_add_u64 v[222:223], s[26:27], 0, v[134:135]
	s_mov_b32 m0, s4
	s_nop 0
	global_load_lds_dwordx4 v[222:223], off
	s_mov_b32 m0, s5
	s_nop 0
	global_load_lds_dwordx4 v[224:225], off
	s_add_i32 s46, 0, 0x18000
	v_add_u32_e32 v157, s46, v151
	s_add_i32 s47, 0, 0x1c000
	ds_read_b128 v[144:147], v157
	ds_read_b128 v[158:161], v157 offset:1024
	ds_read_b128 v[162:165], v157 offset:2048
	ds_read_b128 v[166:169], v157 offset:3072
	v_add_u32_e32 v157, s47, v151
	ds_read_b128 v[170:173], v157
	ds_read_b128 v[174:177], v157 offset:1024
	ds_read_b128 v[178:181], v157 offset:2048
	ds_read_b128 v[182:185], v157 offset:3072
	s_add_u32 s26, s26, 0x40000
	s_addc_u32 s27, s27, 0
	s_mov_b32 m0, s23
	v_lshl_add_u64 v[226:227], s[26:27], 0, v[134:135]
	ds_read_b128 v[186:189], v156 offset:32768
	ds_read_b128 v[190:193], v156 offset:33792
	ds_read_b128 v[196:199], v156 offset:34816
	ds_read_b128 v[200:203], v156 offset:35840
	ds_read_b128 v[204:207], v156 offset:36864
	ds_read_b128 v[208:211], v156 offset:37888
	ds_read_b128 v[212:215], v156 offset:38912
	ds_read_b128 v[216:219], v156 offset:39936
	global_load_lds_dwordx4 v[226:227], off
	v_lshl_add_u64 v[226:227], s[26:27], 0, v[130:131]
	s_mov_b32 m0, s28
	s_nop 0
	global_load_lds_dwordx4 v[226:227], off
	s_waitcnt vmcnt(8)
	s_waitcnt lgkmcnt(0)
	s_barrier
	s_setprio 1
	s_waitcnt lgkmcnt(0)
	v_mfma_f32_16x16x32_bf16 v[124:127], v[144:147], v[186:189], v[124:127]
	v_mfma_f32_16x16x32_bf16 v[120:123], v[162:165], v[186:189], v[120:123]
	v_mfma_f32_16x16x32_bf16 v[108:111], v[144:147], v[196:199], v[108:111]
	v_mfma_f32_16x16x32_bf16 v[104:107], v[162:165], v[196:199], v[104:107]
	v_mfma_f32_16x16x32_bf16 v[92:95], v[144:147], v[204:207], v[92:95]
	v_mfma_f32_16x16x32_bf16 v[88:91], v[162:165], v[204:207], v[88:91]
	v_mfma_f32_16x16x32_bf16 v[76:79], v[144:147], v[212:215], v[76:79]
	v_mfma_f32_16x16x32_bf16 v[72:75], v[162:165], v[212:215], v[72:75]
	v_mfma_f32_16x16x32_bf16 v[124:127], v[158:161], v[190:193], v[124:127]
	v_mfma_f32_16x16x32_bf16 v[120:123], v[166:169], v[190:193], v[120:123]
	v_mfma_f32_16x16x32_bf16 v[108:111], v[158:161], v[200:203], v[108:111]
	v_mfma_f32_16x16x32_bf16 v[104:107], v[166:169], v[200:203], v[104:107]
	v_mfma_f32_16x16x32_bf16 v[92:95], v[158:161], v[208:211], v[92:95]
	v_mfma_f32_16x16x32_bf16 v[88:91], v[166:169], v[208:211], v[88:91]
	v_mfma_f32_16x16x32_bf16 v[76:79], v[158:161], v[216:219], v[76:79]
	v_mfma_f32_16x16x32_bf16 v[72:75], v[166:169], v[216:219], v[72:75]
	s_setprio 0
	s_setprio 1
	v_mfma_f32_16x16x32_bf16 v[116:119], v[170:173], v[186:189], v[116:119]
	v_mfma_f32_16x16x32_bf16 v[112:115], v[178:181], v[186:189], v[112:115]
	v_mfma_f32_16x16x32_bf16 v[100:103], v[170:173], v[196:199], v[100:103]
	v_mfma_f32_16x16x32_bf16 v[96:99], v[178:181], v[196:199], v[96:99]
	v_mfma_f32_16x16x32_bf16 v[84:87], v[170:173], v[204:207], v[84:87]
	v_mfma_f32_16x16x32_bf16 v[80:83], v[178:181], v[204:207], v[80:83]
	v_mfma_f32_16x16x32_bf16 v[68:71], v[170:173], v[212:215], v[68:71]
	v_mfma_f32_16x16x32_bf16 v[64:67], v[178:181], v[212:215], v[64:67]
	v_mfma_f32_16x16x32_bf16 v[116:119], v[174:177], v[190:193], v[116:119]
	v_mfma_f32_16x16x32_bf16 v[112:115], v[182:185], v[190:193], v[112:115]
	v_mfma_f32_16x16x32_bf16 v[100:103], v[174:177], v[200:203], v[100:103]
	v_mfma_f32_16x16x32_bf16 v[96:99], v[182:185], v[200:203], v[96:99]
	v_mfma_f32_16x16x32_bf16 v[84:87], v[174:177], v[208:211], v[84:87]
	v_mfma_f32_16x16x32_bf16 v[80:83], v[182:185], v[208:211], v[80:83]
	v_mfma_f32_16x16x32_bf16 v[68:71], v[174:177], v[216:219], v[68:71]
	v_mfma_f32_16x16x32_bf16 v[64:67], v[182:185], v[216:219], v[64:67]
	s_setprio 0
	s_barrier
	s_add_i32 s26, s46, s3
	v_lshl_add_u64 v[148:149], v[148:149], 0, s[6:7]
	s_mov_b32 m0, s26
	ds_read_b128 v[186:189], v156 offset:49152
	ds_read_b128 v[190:193], v156 offset:50176
	ds_read_b128 v[196:199], v156 offset:51200
	ds_read_b128 v[200:203], v156 offset:52224
	ds_read_b128 v[204:207], v156 offset:53248
	ds_read_b128 v[208:211], v156 offset:54272
	ds_read_b128 v[212:215], v156 offset:55296
	ds_read_b128 v[216:219], v156 offset:56320
	global_load_lds_dwordx4 v[148:149], off
	s_add_i32 m0, s26, 0x2000
	s_add_u32 s8, s8, 0x40080
	v_lshl_add_u64 v[148:149], v[220:221], 0, s[6:7]
	s_addc_u32 s9, s9, 0
	s_add_i32 s26, s47, s3
	global_load_lds_dwordx4 v[148:149], off
	v_lshl_add_u64 v[148:149], s[8:9], 0, v[132:133]
	s_mov_b32 m0, s26
	s_nop 0
	global_load_lds_dwordx4 v[148:149], off
	v_lshl_add_u64 v[148:149], s[8:9], 0, v[128:129]
	s_add_i32 m0, s26, 0x2000
	s_nop 0
	global_load_lds_dwordx4 v[148:149], off
	v_lshl_add_u64 v[148:149], v[222:223], 0, s[6:7]
	s_mov_b32 m0, s29
	s_nop 0
	global_load_lds_dwordx4 v[148:149], off
	v_lshl_add_u64 v[148:149], v[224:225], 0, s[6:7]
	s_mov_b32 m0, s30
	s_nop 0
	global_load_lds_dwordx4 v[148:149], off
	s_waitcnt vmcnt(8)
	s_waitcnt lgkmcnt(0)
	s_barrier
	s_setprio 1
	s_waitcnt lgkmcnt(0)
	v_mfma_f32_16x16x32_bf16 v[60:63], v[144:147], v[186:189], v[60:63]
	v_mfma_f32_16x16x32_bf16 v[56:59], v[162:165], v[186:189], v[56:59]
	v_mfma_f32_16x16x32_bf16 v[44:47], v[144:147], v[196:199], v[44:47]
	v_mfma_f32_16x16x32_bf16 v[40:43], v[162:165], v[196:199], v[40:43]
	v_mfma_f32_16x16x32_bf16 v[28:31], v[144:147], v[204:207], v[28:31]
	v_mfma_f32_16x16x32_bf16 v[24:27], v[162:165], v[204:207], v[24:27]
	v_mfma_f32_16x16x32_bf16 v[12:15], v[144:147], v[212:215], v[12:15]
	v_mfma_f32_16x16x32_bf16 v[8:11], v[162:165], v[212:215], v[8:11]
	v_mfma_f32_16x16x32_bf16 v[60:63], v[158:161], v[190:193], v[60:63]
	v_mfma_f32_16x16x32_bf16 v[56:59], v[166:169], v[190:193], v[56:59]
	v_mfma_f32_16x16x32_bf16 v[44:47], v[158:161], v[200:203], v[44:47]
	v_mfma_f32_16x16x32_bf16 v[40:43], v[166:169], v[200:203], v[40:43]
	v_mfma_f32_16x16x32_bf16 v[28:31], v[158:161], v[208:211], v[28:31]
	v_mfma_f32_16x16x32_bf16 v[24:27], v[166:169], v[208:211], v[24:27]
	v_mfma_f32_16x16x32_bf16 v[12:15], v[158:161], v[216:219], v[12:15]
	v_mfma_f32_16x16x32_bf16 v[8:11], v[166:169], v[216:219], v[8:11]
	s_setprio 0
	s_setprio 1
	v_mfma_f32_16x16x32_bf16 v[52:55], v[170:173], v[186:189], v[52:55]
	v_mfma_f32_16x16x32_bf16 v[48:51], v[178:181], v[186:189], v[48:51]
	v_mfma_f32_16x16x32_bf16 v[36:39], v[170:173], v[196:199], v[36:39]
	v_mfma_f32_16x16x32_bf16 v[32:35], v[178:181], v[196:199], v[32:35]
	v_mfma_f32_16x16x32_bf16 v[20:23], v[170:173], v[204:207], v[20:23]
	v_mfma_f32_16x16x32_bf16 v[16:19], v[178:181], v[204:207], v[16:19]
	v_mfma_f32_16x16x32_bf16 v[4:7], v[170:173], v[212:215], v[4:7]
	v_mfma_f32_16x16x32_bf16 v[0:3], v[178:181], v[212:215], v[0:3]
	v_mfma_f32_16x16x32_bf16 v[52:55], v[174:177], v[190:193], v[52:55]
	v_mfma_f32_16x16x32_bf16 v[48:51], v[182:185], v[190:193], v[48:51]
	v_mfma_f32_16x16x32_bf16 v[36:39], v[174:177], v[200:203], v[36:39]
	v_mfma_f32_16x16x32_bf16 v[32:35], v[182:185], v[200:203], v[32:35]
	v_mfma_f32_16x16x32_bf16 v[20:23], v[174:177], v[208:211], v[20:23]
	v_mfma_f32_16x16x32_bf16 v[16:19], v[182:185], v[208:211], v[16:19]
	v_mfma_f32_16x16x32_bf16 v[4:7], v[174:177], v[216:219], v[4:7]
	v_mfma_f32_16x16x32_bf16 v[0:3], v[182:185], v[216:219], v[0:3]
	s_setprio 0
	s_barrier
	s_add_i32 s45, s45, 2
	s_add_u32 s24, s24, 0x100
	s_addc_u32 s25, s25, 0
	s_add_u32 s41, s41, 0x100
	s_addc_u32 s44, s44, 0
	s_cmp_gt_u32 s45, 13
	s_cbranch_scc0 .LBB0_1325
	s_and_b64 vcc, exec, s[10:11]
	s_cbranch_vccz .LBB0_1328
	s_barrier

.LBB0_1399:
	ds_read_b128 v[144:147], v153
	ds_read_b128 v[156:159], v153 offset:1024
	ds_read_b128 v[160:163], v153 offset:2048
	ds_read_b128 v[164:167], v153 offset:3072
	ds_read_b128 v[168:171], v154
	ds_read_b128 v[172:175], v154 offset:1024
	ds_read_b128 v[176:179], v154 offset:2048
	ds_read_b128 v[180:183], v154 offset:3072
	s_add_u32 s36, s34, 0xfff00080
	s_addc_u32 s37, s35, -1
	s_cmp_eq_u32 s50, 60
	s_cselect_b32 s39, s25, s37
	s_cselect_b32 s38, s46, s36
	s_cselect_b32 s37, s23, s49
	s_cselect_b32 s36, s47, s48
	v_lshl_add_u64 v[148:149], s[34:35], 0, v[136:137]
	s_add_i32 m0, s4, 0xc000
	ds_read_b128 v[184:187], v155
	ds_read_b128 v[188:191], v155 offset:1024
	ds_read_b128 v[192:195], v155 offset:2048
	ds_read_b128 v[196:199], v155 offset:3072
	ds_read_b128 v[200:203], v155 offset:4096
	ds_read_b128 v[204:207], v155 offset:5120
	ds_read_b128 v[208:211], v155 offset:6144
	ds_read_b128 v[212:215], v155 offset:7168
	global_load_lds_dwordx4 v[148:149], off
	v_lshl_add_u64 v[148:149], s[34:35], 0, v[138:139]
	s_add_i32 m0, s4, 0xe000
	s_nop 0
	global_load_lds_dwordx4 v[148:149], off
	s_waitcnt vmcnt(8)
	s_waitcnt lgkmcnt(0)
	s_barrier
	s_setprio 1
	s_waitcnt lgkmcnt(0)
	v_mfma_f32_16x16x32_bf16 v[124:127], v[144:147], v[184:187], v[124:127]
	v_mfma_f32_16x16x32_bf16 v[120:123], v[160:163], v[184:187], v[120:123]
	v_mfma_f32_16x16x32_bf16 v[108:111], v[144:147], v[192:195], v[108:111]
	v_mfma_f32_16x16x32_bf16 v[104:107], v[160:163], v[192:195], v[104:107]
	v_mfma_f32_16x16x32_bf16 v[92:95], v[144:147], v[200:203], v[92:95]
	v_mfma_f32_16x16x32_bf16 v[88:91], v[160:163], v[200:203], v[88:91]
	v_mfma_f32_16x16x32_bf16 v[76:79], v[144:147], v[208:211], v[76:79]
	v_mfma_f32_16x16x32_bf16 v[72:75], v[160:163], v[208:211], v[72:75]
	v_mfma_f32_16x16x32_bf16 v[124:127], v[156:159], v[188:191], v[124:127]
	v_mfma_f32_16x16x32_bf16 v[120:123], v[164:167], v[188:191], v[120:123]
	v_mfma_f32_16x16x32_bf16 v[108:111], v[156:159], v[196:199], v[108:111]
	v_mfma_f32_16x16x32_bf16 v[104:107], v[164:167], v[196:199], v[104:107]
	v_mfma_f32_16x16x32_bf16 v[92:95], v[156:159], v[204:207], v[92:95]
	v_mfma_f32_16x16x32_bf16 v[88:91], v[164:167], v[204:207], v[88:91]
	v_mfma_f32_16x16x32_bf16 v[76:79], v[156:159], v[212:215], v[76:79]
	v_mfma_f32_16x16x32_bf16 v[72:75], v[164:167], v[212:215], v[72:75]
	s_setprio 0
	s_setprio 1
	v_mfma_f32_16x16x32_bf16 v[116:119], v[168:171], v[184:187], v[116:119]
	v_mfma_f32_16x16x32_bf16 v[112:115], v[176:179], v[184:187], v[112:115]
	v_mfma_f32_16x16x32_bf16 v[100:103], v[168:171], v[192:195], v[100:103]
	v_mfma_f32_16x16x32_bf16 v[96:99], v[176:179], v[192:195], v[96:99]
	v_mfma_f32_16x16x32_bf16 v[84:87], v[168:171], v[200:203], v[84:87]
	v_mfma_f32_16x16x32_bf16 v[80:83], v[176:179], v[200:203], v[80:83]
	v_mfma_f32_16x16x32_bf16 v[68:71], v[168:171], v[208:211], v[68:71]
	v_mfma_f32_16x16x32_bf16 v[64:67], v[176:179], v[208:211], v[64:67]
	v_mfma_f32_16x16x32_bf16 v[116:119], v[172:175], v[188:191], v[116:119]
	v_mfma_f32_16x16x32_bf16 v[112:115], v[180:183], v[188:191], v[112:115]
	v_mfma_f32_16x16x32_bf16 v[100:103], v[172:175], v[196:199], v[100:103]
	v_mfma_f32_16x16x32_bf16 v[96:99], v[180:183], v[196:199], v[96:99]
	v_mfma_f32_16x16x32_bf16 v[84:87], v[172:175], v[204:207], v[84:87]
	v_mfma_f32_16x16x32_bf16 v[80:83], v[180:183], v[204:207], v[80:83]
	v_mfma_f32_16x16x32_bf16 v[68:71], v[172:175], v[212:215], v[68:71]
	v_mfma_f32_16x16x32_bf16 v[64:67], v[180:183], v[212:215], v[64:67]
	s_setprio 0
	s_barrier
	s_add_i32 s51, s43, s3
	v_lshl_add_u64 v[148:149], s[36:37], 0, v[132:133]
	s_mov_b32 m0, s51
	ds_read_b128 v[184:187], v155 offset:16384
	ds_read_b128 v[188:191], v155 offset:17408
	ds_read_b128 v[192:195], v155 offset:18432
	ds_read_b128 v[196:199], v155 offset:19456
	ds_read_b128 v[200:203], v155 offset:20480
	ds_read_b128 v[204:207], v155 offset:21504
	ds_read_b128 v[208:211], v155 offset:22528
	ds_read_b128 v[212:215], v155 offset:23552
	global_load_lds_dwordx4 v[148:149], off
	s_add_i32 m0, s51, 0x2000
	s_add_u32 s52, s36, 0x100000
	v_lshl_add_u64 v[216:217], s[36:37], 0, v[128:129]
	s_addc_u32 s53, s37, 0
	s_add_i32 s51, s44, s3
	global_load_lds_dwordx4 v[216:217], off
	v_lshl_add_u64 v[218:219], s[52:53], 0, v[132:133]
	s_mov_b32 m0, s51
	v_lshl_add_u64 v[220:221], s[38:39], 0, v[130:131]
	global_load_lds_dwordx4 v[218:219], off
	v_lshl_add_u64 v[218:219], s[52:53], 0, v[128:129]
	s_add_i32 m0, s51, 0x2000
	s_nop 0
	global_load_lds_dwordx4 v[218:219], off
	s_waitcnt vmcnt(6)
	s_waitcnt lgkmcnt(0)
	s_barrier
	s_setprio 1
	s_waitcnt lgkmcnt(0)
	v_mfma_f32_16x16x32_bf16 v[60:63], v[144:147], v[184:187], v[60:63]
	v_mfma_f32_16x16x32_bf16 v[56:59], v[160:163], v[184:187], v[56:59]
	v_mfma_f32_16x16x32_bf16 v[44:47], v[144:147], v[192:195], v[44:47]
	v_mfma_f32_16x16x32_bf16 v[40:43], v[160:163], v[192:195], v[40:43]
	v_mfma_f32_16x16x32_bf16 v[28:31], v[144:147], v[200:203], v[28:31]
	v_mfma_f32_16x16x32_bf16 v[24:27], v[160:163], v[200:203], v[24:27]
	v_mfma_f32_16x16x32_bf16 v[12:15], v[144:147], v[208:211], v[12:15]
	v_mfma_f32_16x16x32_bf16 v[8:11], v[160:163], v[208:211], v[8:11]
	v_mfma_f32_16x16x32_bf16 v[60:63], v[156:159], v[188:191], v[60:63]
	v_mfma_f32_16x16x32_bf16 v[56:59], v[164:167], v[188:191], v[56:59]
	v_mfma_f32_16x16x32_bf16 v[44:47], v[156:159], v[196:199], v[44:47]
	v_mfma_f32_16x16x32_bf16 v[40:43], v[164:167], v[196:199], v[40:43]
	v_mfma_f32_16x16x32_bf16 v[28:31], v[156:159], v[204:207], v[28:31]
	v_mfma_f32_16x16x32_bf16 v[24:27], v[164:167], v[204:207], v[24:27]
	v_mfma_f32_16x16x32_bf16 v[12:15], v[156:159], v[212:215], v[12:15]
	v_mfma_f32_16x16x32_bf16 v[8:11], v[164:167], v[212:215], v[8:11]
	s_setprio 0
	s_setprio 1
	v_mfma_f32_16x16x32_bf16 v[52:55], v[168:171], v[184:187], v[52:55]
	v_mfma_f32_16x16x32_bf16 v[48:51], v[176:179], v[184:187], v[48:51]
	v_mfma_f32_16x16x32_bf16 v[36:39], v[168:171], v[192:195], v[36:39]
	v_mfma_f32_16x16x32_bf16 v[32:35], v[176:179], v[192:195], v[32:35]
	v_mfma_f32_16x16x32_bf16 v[20:23], v[168:171], v[200:203], v[20:23]
	v_mfma_f32_16x16x32_bf16 v[16:19], v[176:179], v[200:203], v[16:19]
	v_mfma_f32_16x16x32_bf16 v[4:7], v[168:171], v[208:211], v[4:7]
	v_mfma_f32_16x16x32_bf16 v[0:3], v[176:179], v[208:211], v[0:3]
	v_mfma_f32_16x16x32_bf16 v[52:55], v[172:175], v[188:191], v[52:55]
	v_mfma_f32_16x16x32_bf16 v[48:51], v[180:183], v[188:191], v[48:51]
	v_mfma_f32_16x16x32_bf16 v[36:39], v[172:175], v[196:199], v[36:39]
	v_mfma_f32_16x16x32_bf16 v[32:35], v[180:183], v[196:199], v[32:35]
	v_mfma_f32_16x16x32_bf16 v[20:23], v[172:175], v[204:207], v[20:23]
	v_mfma_f32_16x16x32_bf16 v[16:19], v[180:183], v[204:207], v[16:19]
	v_mfma_f32_16x16x32_bf16 v[4:7], v[172:175], v[212:215], v[4:7]
	v_mfma_f32_16x16x32_bf16 v[0:3], v[180:183], v[212:215], v[0:3]
	s_setprio 0
	s_barrier
	v_lshl_add_u64 v[218:219], s[38:39], 0, v[134:135]
	s_mov_b32 m0, s4
	s_nop 0
	global_load_lds_dwordx4 v[218:219], off
	s_mov_b32 m0, s5
	s_nop 0
	global_load_lds_dwordx4 v[220:221], off
	s_add_i32 s51, 0, 0x18000
	s_add_i32 s52, 0, 0x1c000
	v_add_u32_e32 v164, s51, v151
	v_add_u32_e32 v180, s52, v151
	ds_read_b128 v[144:147], v164
	ds_read_b128 v[156:159], v164 offset:1024
	ds_read_b128 v[160:163], v164 offset:2048
	ds_read_b128 v[164:167], v164 offset:3072
	ds_read_b128 v[168:171], v180
	ds_read_b128 v[172:175], v180 offset:1024
	ds_read_b128 v[176:179], v180 offset:2048
	ds_read_b128 v[180:183], v180 offset:3072
	s_add_u32 s38, s38, 0x100000
	s_addc_u32 s39, s39, 0
	s_mov_b32 m0, s31
	v_lshl_add_u64 v[222:223], s[38:39], 0, v[134:135]
	ds_read_b128 v[184:187], v155 offset:32768
	ds_read_b128 v[188:191], v155 offset:33792
	ds_read_b128 v[192:195], v155 offset:34816
	ds_read_b128 v[196:199], v155 offset:35840
	ds_read_b128 v[200:203], v155 offset:36864
	ds_read_b128 v[204:207], v155 offset:37888
	ds_read_b128 v[208:211], v155 offset:38912
	ds_read_b128 v[212:215], v155 offset:39936
	global_load_lds_dwordx4 v[222:223], off
	v_lshl_add_u64 v[222:223], s[38:39], 0, v[130:131]
	s_mov_b32 m0, s33
	s_nop 0
	global_load_lds_dwordx4 v[222:223], off
	s_waitcnt vmcnt(8)
	s_waitcnt lgkmcnt(0)
	s_barrier
	s_setprio 1
	s_waitcnt lgkmcnt(0)
	v_mfma_f32_16x16x32_bf16 v[124:127], v[144:147], v[184:187], v[124:127]
	v_mfma_f32_16x16x32_bf16 v[120:123], v[160:163], v[184:187], v[120:123]
	v_mfma_f32_16x16x32_bf16 v[108:111], v[144:147], v[192:195], v[108:111]
	v_mfma_f32_16x16x32_bf16 v[104:107], v[160:163], v[192:195], v[104:107]
	v_mfma_f32_16x16x32_bf16 v[92:95], v[144:147], v[200:203], v[92:95]
	v_mfma_f32_16x16x32_bf16 v[88:91], v[160:163], v[200:203], v[88:91]
	v_mfma_f32_16x16x32_bf16 v[76:79], v[144:147], v[208:211], v[76:79]
	v_mfma_f32_16x16x32_bf16 v[72:75], v[160:163], v[208:211], v[72:75]
	v_mfma_f32_16x16x32_bf16 v[124:127], v[156:159], v[188:191], v[124:127]
	v_mfma_f32_16x16x32_bf16 v[120:123], v[164:167], v[188:191], v[120:123]
	v_mfma_f32_16x16x32_bf16 v[108:111], v[156:159], v[196:199], v[108:111]
	v_mfma_f32_16x16x32_bf16 v[104:107], v[164:167], v[196:199], v[104:107]
	v_mfma_f32_16x16x32_bf16 v[92:95], v[156:159], v[204:207], v[92:95]
	v_mfma_f32_16x16x32_bf16 v[88:91], v[164:167], v[204:207], v[88:91]
	v_mfma_f32_16x16x32_bf16 v[76:79], v[156:159], v[212:215], v[76:79]
	v_mfma_f32_16x16x32_bf16 v[72:75], v[164:167], v[212:215], v[72:75]
	s_setprio 0
	s_setprio 1
	v_mfma_f32_16x16x32_bf16 v[116:119], v[168:171], v[184:187], v[116:119]
	v_mfma_f32_16x16x32_bf16 v[112:115], v[176:179], v[184:187], v[112:115]
	v_mfma_f32_16x16x32_bf16 v[100:103], v[168:171], v[192:195], v[100:103]
	v_mfma_f32_16x16x32_bf16 v[96:99], v[176:179], v[192:195], v[96:99]
	v_mfma_f32_16x16x32_bf16 v[84:87], v[168:171], v[200:203], v[84:87]
	v_mfma_f32_16x16x32_bf16 v[80:83], v[176:179], v[200:203], v[80:83]
	v_mfma_f32_16x16x32_bf16 v[68:71], v[168:171], v[208:211], v[68:71]
	v_mfma_f32_16x16x32_bf16 v[64:67], v[176:179], v[208:211], v[64:67]
	v_mfma_f32_16x16x32_bf16 v[116:119], v[172:175], v[188:191], v[116:119]
	v_mfma_f32_16x16x32_bf16 v[112:115], v[180:183], v[188:191], v[112:115]
	v_mfma_f32_16x16x32_bf16 v[100:103], v[172:175], v[196:199], v[100:103]
	v_mfma_f32_16x16x32_bf16 v[96:99], v[180:183], v[196:199], v[96:99]
	v_mfma_f32_16x16x32_bf16 v[84:87], v[172:175], v[204:207], v[84:87]
	v_mfma_f32_16x16x32_bf16 v[80:83], v[180:183], v[204:207], v[80:83]
	v_mfma_f32_16x16x32_bf16 v[68:71], v[172:175], v[212:215], v[68:71]
	v_mfma_f32_16x16x32_bf16 v[64:67], v[180:183], v[212:215], v[64:67]
	s_setprio 0
	s_barrier
	s_add_i32 s38, s51, s3
	v_lshl_add_u64 v[148:149], v[148:149], 0, s[8:9]
	s_mov_b32 m0, s38
	ds_read_b128 v[184:187], v155 offset:49152
	ds_read_b128 v[188:191], v155 offset:50176
	ds_read_b128 v[192:195], v155 offset:51200
	ds_read_b128 v[196:199], v155 offset:52224
	ds_read_b128 v[200:203], v155 offset:53248
	ds_read_b128 v[204:207], v155 offset:54272
	ds_read_b128 v[208:211], v155 offset:55296
	ds_read_b128 v[212:215], v155 offset:56320
	global_load_lds_dwordx4 v[148:149], off
	s_add_i32 m0, s38, 0x2000
	s_add_u32 s36, s36, 0x100080
	v_lshl_add_u64 v[148:149], v[216:217], 0, s[8:9]
	s_addc_u32 s37, s37, 0
	s_add_i32 s38, s52, s3
	global_load_lds_dwordx4 v[148:149], off
	v_lshl_add_u64 v[148:149], s[36:37], 0, v[132:133]
	s_mov_b32 m0, s38
	s_nop 0
	global_load_lds_dwordx4 v[148:149], off
	v_lshl_add_u64 v[148:149], s[36:37], 0, v[128:129]
	s_add_i32 m0, s38, 0x2000
	s_nop 0
	global_load_lds_dwordx4 v[148:149], off
	v_lshl_add_u64 v[148:149], v[218:219], 0, s[8:9]
	s_mov_b32 m0, s41
	s_nop 0
	global_load_lds_dwordx4 v[148:149], off
	v_lshl_add_u64 v[148:149], v[220:221], 0, s[8:9]
	s_mov_b32 m0, s42
	s_nop 0
	global_load_lds_dwordx4 v[148:149], off
	s_waitcnt vmcnt(8)
	s_waitcnt lgkmcnt(0)
	s_barrier
	s_setprio 1
	s_waitcnt lgkmcnt(0)
	v_mfma_f32_16x16x32_bf16 v[60:63], v[144:147], v[184:187], v[60:63]
	v_mfma_f32_16x16x32_bf16 v[56:59], v[160:163], v[184:187], v[56:59]
	v_mfma_f32_16x16x32_bf16 v[44:47], v[144:147], v[192:195], v[44:47]
	v_mfma_f32_16x16x32_bf16 v[40:43], v[160:163], v[192:195], v[40:43]
	v_mfma_f32_16x16x32_bf16 v[28:31], v[144:147], v[200:203], v[28:31]
	v_mfma_f32_16x16x32_bf16 v[24:27], v[160:163], v[200:203], v[24:27]
	v_mfma_f32_16x16x32_bf16 v[12:15], v[144:147], v[208:211], v[12:15]
	v_mfma_f32_16x16x32_bf16 v[8:11], v[160:163], v[208:211], v[8:11]
	v_mfma_f32_16x16x32_bf16 v[60:63], v[156:159], v[188:191], v[60:63]
	v_mfma_f32_16x16x32_bf16 v[56:59], v[164:167], v[188:191], v[56:59]
	v_mfma_f32_16x16x32_bf16 v[44:47], v[156:159], v[196:199], v[44:47]
	v_mfma_f32_16x16x32_bf16 v[40:43], v[164:167], v[196:199], v[40:43]
	v_mfma_f32_16x16x32_bf16 v[28:31], v[156:159], v[204:207], v[28:31]
	v_mfma_f32_16x16x32_bf16 v[24:27], v[164:167], v[204:207], v[24:27]
	v_mfma_f32_16x16x32_bf16 v[12:15], v[156:159], v[212:215], v[12:15]
	v_mfma_f32_16x16x32_bf16 v[8:11], v[164:167], v[212:215], v[8:11]
	s_setprio 0
	s_setprio 1
	v_mfma_f32_16x16x32_bf16 v[52:55], v[168:171], v[184:187], v[52:55]
	v_mfma_f32_16x16x32_bf16 v[48:51], v[176:179], v[184:187], v[48:51]
	v_mfma_f32_16x16x32_bf16 v[36:39], v[168:171], v[192:195], v[36:39]
	v_mfma_f32_16x16x32_bf16 v[32:35], v[176:179], v[192:195], v[32:35]
	v_mfma_f32_16x16x32_bf16 v[20:23], v[168:171], v[200:203], v[20:23]
	v_mfma_f32_16x16x32_bf16 v[16:19], v[176:179], v[200:203], v[16:19]
	v_mfma_f32_16x16x32_bf16 v[4:7], v[168:171], v[208:211], v[4:7]
	v_mfma_f32_16x16x32_bf16 v[0:3], v[176:179], v[208:211], v[0:3]
	v_mfma_f32_16x16x32_bf16 v[52:55], v[172:175], v[188:191], v[52:55]
	v_mfma_f32_16x16x32_bf16 v[48:51], v[180:183], v[188:191], v[48:51]
	v_mfma_f32_16x16x32_bf16 v[36:39], v[172:175], v[196:199], v[36:39]
	v_mfma_f32_16x16x32_bf16 v[32:35], v[180:183], v[196:199], v[32:35]
	v_mfma_f32_16x16x32_bf16 v[20:23], v[172:175], v[204:207], v[20:23]
	v_mfma_f32_16x16x32_bf16 v[16:19], v[180:183], v[204:207], v[16:19]
	v_mfma_f32_16x16x32_bf16 v[4:7], v[172:175], v[212:215], v[4:7]
	v_mfma_f32_16x16x32_bf16 v[0:3], v[180:183], v[212:215], v[0:3]
	s_setprio 0
	s_barrier
	s_add_i32 s50, s50, 2
	s_add_u32 s34, s34, 0x100
	s_addc_u32 s35, s35, 0
	s_add_u32 s48, s48, 0x100
	s_addc_u32 s49, s49, 0
	s_cmp_gt_u32 s50, 61
	s_cbranch_scc0 .LBB0_1399
	s_and_b64 vcc, exec, s[10:11]
	s_cbranch_vccz .LBB0_1402
	s_barrier
